# dead pointer s_loads removed from the GDN prep conv taps and the SGU group loop; LRU pass-2 setup issues its three halo loads together
# baseline (speedup 1.0000x reference)
.LBB0_680:
	s_mov_b32 s4, 0
	s_ashr_i32 s5, s4, 31
	s_lshl_b64 s[4:5], s[4:5], 3
	v_lshl_add_u64 v[0:1], s[90:91], 0, v[34:35]
	s_add_u32 s4, s0, s4
	v_add_co_u32_e32 v6, vcc, s86, v0
	s_addc_u32 s5, s1, s5
	s_nop 0
	v_addc_co_u32_e32 v7, vcc, 0, v1, vcc
	s_load_dwordx2 s[4:5], s[4:5], 0x38
	s_load_dwordx2 s[98:99], s[0:1], 0x48
	s_load_dwordx2 s[100:101], s[0:1], 0x50
	s_mov_b32 s8, 0
	s_ashr_i32 s9, s8, 31
	s_lshl_b64 s[8:9], s[8:9], 3
	s_add_u32 s8, s0, s8
	s_addc_u32 s9, s1, s9
	s_load_dwordx2 s[8:9], s[8:9], 0x40
	s_mov_b32 s2, 0x190c0000
	s_waitcnt lgkmcnt(0)
	v_lshl_add_u64 v[70:71], s[4:5], 0, v[40:41]
	v_lshl_add_u64 v[72:73], s[8:9], 0, v[40:41]
	v_lshl_add_u64 v[70:71], v[70:71], 0, s[42:43]
	v_lshl_add_u64 v[72:73], v[72:73], 0, s[42:43]
	v_lshl_add_u64 v[74:75], s[98:99], 0, v[42:43]
	v_lshl_add_u64 v[76:77], s[100:101], 0, v[44:45]
	v_lshl_add_u64 v[194:195], s[90:91], 0, v[48:49]
	v_lshl_add_u64 v[76:77], v[76:77], 0, s[42:43]
	v_add_co_u32_e32 v194, vcc, s86, v194
	s_nop 1
	v_addc_co_u32_e32 v195, vcc, 0, v195, vcc
	global_load_dwordx4 v[82:85], v[6:7], off offset:1024
	global_load_dwordx4 v[130:133], v[72:73], off
	global_load_dwordx4 v[98:101], v[70:71], off
	global_load_dwordx4 v[102:105], v[70:71], off offset:16
	global_load_dwordx4 v[134:137], v[72:73], off offset:16
	global_load_dwordx4 v[86:89], v[6:7], off offset:1088
	global_load_dwordx4 v[106:109], v[70:71], off offset:128
	global_load_dwordx4 v[138:141], v[72:73], off offset:128
	global_load_dwordx4 v[110:113], v[70:71], off offset:144
	global_load_dwordx4 v[142:145], v[72:73], off offset:144
	global_load_dwordx4 v[90:93], v[6:7], off offset:1152
	global_load_dwordx4 v[114:117], v[70:71], off offset:256
	global_load_dwordx4 v[146:149], v[72:73], off offset:256
	global_load_dwordx4 v[118:121], v[70:71], off offset:272
	global_load_dwordx4 v[150:153], v[72:73], off offset:272
	global_load_dwordx4 v[94:97], v[6:7], off offset:1216
	global_load_dwordx4 v[122:125], v[70:71], off offset:384
	global_load_dwordx4 v[154:157], v[72:73], off offset:384
	global_load_dwordx4 v[126:129], v[70:71], off offset:400
	global_load_dwordx4 v[158:161], v[72:73], off offset:400
	global_load_dwordx4 v[162:165], v[74:75], off offset:-64
	global_load_dwordx4 v[166:169], v[74:75], off offset:-48
	global_load_dwordx4 v[170:173], v[74:75], off offset:-32
	global_load_dwordx4 v[174:177], v[74:75], off offset:-16
	global_load_dwordx4 v[178:181], v[74:75], off
	global_load_dwordx4 v[182:185], v[74:75], off offset:16
	global_load_dwordx4 v[186:189], v[74:75], off offset:32
	global_load_dwordx4 v[190:193], v[74:75], off offset:48
	global_load_dword v224, v[76:77], off
	global_load_dwordx2 v[208:209], v[194:195], off
	global_load_dwordx2 v[210:211], v[194:195], off offset:32
	global_load_dwordx2 v[212:213], v[194:195], off offset:64
	global_load_dwordx2 v[214:215], v[194:195], off offset:96
	global_load_dwordx2 v[216:217], v[194:195], off offset:128
	global_load_dwordx2 v[218:219], v[194:195], off offset:160
	global_load_dwordx2 v[220:221], v[194:195], off offset:192
	global_load_dwordx2 v[222:223], v[194:195], off offset:224
	s_waitcnt vmcnt(0)
	v_mov_b64_e32 v[0:1], v[82:83]
	v_mov_b64_e32 v[2:3], v[84:85]
	v_lshl_add_u64 v[8:9], s[8:9], 0, v[40:41]
	v_lshl_add_u64 v[8:9], v[8:9], 0, s[42:43]
	v_mov_b64_e32 v[18:19], v[130:131]
	v_mov_b64_e32 v[20:21], v[132:133]
	v_lshlrev_b32_e32 v4, 16, v0
	v_mul_f32_e32 v5, 0x3d372713, v4
	v_mul_f32_e32 v5, v5, v4
	v_fma_f32 v5, v5, v4, v4
	v_mul_f32_e32 v5, 0xbfcc422a, v5
	v_mul_f32_e32 v5, 0x3fb8aa3b, v5
	v_exp_f32_e32 v5, v5
	v_and_b32_e32 v0, 0xffff0000, v0
	v_add_f32_e32 v5, 1.0, v5
	v_rcp_f32_e32 v5, v5
	s_nop 0
	v_fma_f32 v4, v5, v4, -v37
	v_mul_f32_e32 v14, v36, v4
	v_lshl_add_u64 v[4:5], s[4:5], 0, v[40:41]
	v_lshl_add_u64 v[4:5], v[4:5], 0, s[42:43]
	v_mov_b64_e32 v[10:11], v[98:99]
	v_mov_b64_e32 v[12:13], v[100:101]
	v_fma_f32 v10, v10, v14, v18
	v_cvt_pk_bf16_f32 v10, v10, v17
	ds_write_b16 v16, v10 offset:34816
	v_mul_f32_e32 v10, 0x3d372713, v0
	v_mul_f32_e32 v10, v10, v0
	v_fma_f32 v10, v10, v0, v0
	v_mul_f32_e32 v10, 0xbfcc422a, v10
	v_mul_f32_e32 v10, 0x3fb8aa3b, v10
	v_exp_f32_e32 v10, v10
	s_nop 0
	v_add_f32_e32 v10, 1.0, v10
	v_rcp_f32_e32 v10, v10
	s_nop 0
	v_fma_f32 v0, v10, v0, -v37
	v_mul_f32_e32 v0, v36, v0
	v_fma_f32 v0, v11, v0, v19
	v_cvt_pk_bf16_f32 v0, v0, v17
	ds_write_b16 v39, v0 offset:34816
	v_lshlrev_b32_e32 v0, 16, v1
	v_mul_f32_e32 v10, 0x3d372713, v0
	v_mul_f32_e32 v10, v10, v0
	v_fma_f32 v10, v10, v0, v0
	v_mul_f32_e32 v10, 0xbfcc422a, v10
	v_mul_f32_e32 v10, 0x3fb8aa3b, v10
	v_exp_f32_e32 v10, v10
	s_nop 0
	v_add_f32_e32 v10, 1.0, v10
	v_rcp_f32_e32 v10, v10
	s_nop 0
	v_fma_f32 v0, v10, v0, -v37
	v_mul_f32_e32 v0, v36, v0
	v_fma_f32 v0, v12, v0, v20
	v_cvt_pk_bf16_f32 v0, v0, v17
	ds_write_b16 v39, v0 offset:35088
	v_and_b32_e32 v0, 0xffff0000, v1
	v_mul_f32_e32 v1, 0x3d372713, v0
	v_mul_f32_e32 v1, v1, v0
	v_fma_f32 v1, v1, v0, v0
	v_mul_f32_e32 v1, 0xbfcc422a, v1
	v_mul_f32_e32 v1, 0x3fb8aa3b, v1
	v_exp_f32_e32 v1, v1
	s_nop 0
	v_add_f32_e32 v1, 1.0, v1
	v_rcp_f32_e32 v1, v1
	s_nop 0
	v_fma_f32 v0, v1, v0, -v37
	v_mul_f32_e32 v0, v36, v0
	v_fmac_f32_e32 v21, v13, v0
	v_cvt_pk_bf16_f32 v0, v21, v17
	ds_write_b16 v39, v0 offset:35360
	v_mov_b64_e32 v[10:11], v[102:103]
	v_mov_b64_e32 v[12:13], v[104:105]
	v_mov_b64_e32 v[18:19], v[134:135]
	v_mov_b64_e32 v[20:21], v[136:137]
	v_lshlrev_b32_e32 v0, 16, v2
	v_mul_f32_e32 v1, 0x3d372713, v0
	v_mul_f32_e32 v1, v1, v0
	v_fma_f32 v1, v1, v0, v0
	v_mul_f32_e32 v1, 0xbfcc422a, v1
	v_mul_f32_e32 v1, 0x3fb8aa3b, v1
	v_exp_f32_e32 v1, v1
	s_nop 0
	v_add_f32_e32 v1, 1.0, v1
	v_rcp_f32_e32 v1, v1
	s_nop 0
	v_fma_f32 v0, v1, v0, -v37
	v_mul_f32_e32 v0, v36, v0
	s_waitcnt vmcnt(0)
	v_fma_f32 v0, v0, v10, v18
	v_cvt_pk_bf16_f32 v0, v0, v17
	ds_write_b16 v39, v0 offset:35632
	v_and_b32_e32 v0, 0xffff0000, v2
	v_mul_f32_e32 v1, 0x3d372713, v0
	v_mul_f32_e32 v1, v1, v0
	v_fma_f32 v1, v1, v0, v0
	v_mul_f32_e32 v1, 0xbfcc422a, v1
	v_mul_f32_e32 v1, 0x3fb8aa3b, v1
	v_exp_f32_e32 v1, v1
	s_nop 0
	v_add_f32_e32 v1, 1.0, v1
	v_rcp_f32_e32 v1, v1
	s_nop 0
	v_fma_f32 v0, v1, v0, -v37
	v_mul_f32_e32 v0, v36, v0
	v_fma_f32 v0, v0, v11, v19
	v_cvt_pk_bf16_f32 v0, v0, v17
	ds_write_b16 v39, v0 offset:35904
	v_lshlrev_b32_e32 v0, 16, v3
	v_mul_f32_e32 v1, 0x3d372713, v0
	v_mul_f32_e32 v1, v1, v0
	v_fma_f32 v1, v1, v0, v0
	v_mul_f32_e32 v1, 0xbfcc422a, v1
	v_mul_f32_e32 v1, 0x3fb8aa3b, v1
	v_exp_f32_e32 v1, v1
	s_nop 0
	v_add_f32_e32 v1, 1.0, v1
	v_rcp_f32_e32 v1, v1
	s_nop 0
	v_fma_f32 v0, v1, v0, -v37
	v_mul_f32_e32 v0, v36, v0
	v_fma_f32 v0, v0, v12, v20
	v_cvt_pk_bf16_f32 v0, v0, v17
	ds_write_b16 v39, v0 offset:36176
	v_and_b32_e32 v0, 0xffff0000, v3
	v_mul_f32_e32 v1, 0x3d372713, v0
	v_mul_f32_e32 v1, v1, v0
	v_fma_f32 v1, v1, v0, v0
	v_mul_f32_e32 v1, 0xbfcc422a, v1
	v_mul_f32_e32 v1, 0x3fb8aa3b, v1
	v_exp_f32_e32 v1, v1
	s_nop 0
	v_add_f32_e32 v1, 1.0, v1
	v_rcp_f32_e32 v1, v1
	s_nop 0
	v_fma_f32 v0, v1, v0, -v37
	v_mul_f32_e32 v0, v36, v0
	v_fmac_f32_e32 v21, v0, v13
	v_cvt_pk_bf16_f32 v0, v21, v17
	ds_write_b16 v39, v0 offset:36448
	v_mov_b64_e32 v[0:1], v[86:87]
	v_mov_b64_e32 v[2:3], v[88:89]
	s_waitcnt lgkmcnt(0)
	v_lshlrev_b32_e32 v10, 16, v0
	v_mul_f32_e32 v11, 0x3d372713, v10
	v_mul_f32_e32 v11, v11, v10
	v_fma_f32 v11, v11, v10, v10
	v_mul_f32_e32 v11, 0xbfcc422a, v11
	v_mul_f32_e32 v11, 0x3fb8aa3b, v11
	v_exp_f32_e32 v11, v11
	v_and_b32_e32 v0, 0xffff0000, v0
	v_add_f32_e32 v11, 1.0, v11
	v_rcp_f32_e32 v11, v11
	s_nop 0
	v_fma_f32 v10, v11, v10, -v37
	v_mul_f32_e32 v14, v36, v10
	v_mov_b64_e32 v[10:11], v[106:107]
	v_mov_b64_e32 v[12:13], v[108:109]
	v_mov_b64_e32 v[18:19], v[138:139]
	v_mov_b64_e32 v[20:21], v[140:141]
	v_fma_f32 v10, v10, v14, v18
	v_cvt_pk_bf16_f32 v10, v10, v17
	ds_write_b16 v39, v10 offset:43248
	v_mul_f32_e32 v10, 0x3d372713, v0
	v_mul_f32_e32 v10, v10, v0
	v_fma_f32 v10, v10, v0, v0
	v_mul_f32_e32 v10, 0xbfcc422a, v10
	v_mul_f32_e32 v10, 0x3fb8aa3b, v10
	v_exp_f32_e32 v10, v10
	s_nop 0
	v_add_f32_e32 v10, 1.0, v10
	v_rcp_f32_e32 v10, v10
	s_nop 0
	v_fma_f32 v0, v10, v0, -v37
	v_mul_f32_e32 v0, v36, v0
	v_fma_f32 v0, v11, v0, v19
	v_cvt_pk_bf16_f32 v0, v0, v17
	ds_write_b16 v39, v0 offset:43520
	v_lshlrev_b32_e32 v0, 16, v1
	v_mul_f32_e32 v10, 0x3d372713, v0
	v_mul_f32_e32 v10, v10, v0
	v_fma_f32 v10, v10, v0, v0
	v_mul_f32_e32 v10, 0xbfcc422a, v10
	v_mul_f32_e32 v10, 0x3fb8aa3b, v10
	v_exp_f32_e32 v10, v10
	s_nop 0
	v_add_f32_e32 v10, 1.0, v10
	v_rcp_f32_e32 v10, v10
	s_nop 0
	v_fma_f32 v0, v10, v0, -v37
	v_mul_f32_e32 v0, v36, v0
	v_fma_f32 v0, v12, v0, v20
	v_cvt_pk_bf16_f32 v0, v0, v17
	ds_write_b16 v39, v0 offset:43792
	v_and_b32_e32 v0, 0xffff0000, v1
	v_mul_f32_e32 v1, 0x3d372713, v0
	v_mul_f32_e32 v1, v1, v0
	v_fma_f32 v1, v1, v0, v0
	v_mul_f32_e32 v1, 0xbfcc422a, v1
	v_mul_f32_e32 v1, 0x3fb8aa3b, v1
	v_exp_f32_e32 v1, v1
	s_nop 0
	v_add_f32_e32 v1, 1.0, v1
	v_rcp_f32_e32 v1, v1
	s_nop 0
	v_fma_f32 v0, v1, v0, -v37
	v_mul_f32_e32 v0, v36, v0
	v_fmac_f32_e32 v21, v13, v0
	v_cvt_pk_bf16_f32 v0, v21, v17
	ds_write_b16 v39, v0 offset:44064
	v_mov_b64_e32 v[10:11], v[110:111]
	v_mov_b64_e32 v[12:13], v[112:113]
	v_mov_b64_e32 v[18:19], v[142:143]
	v_mov_b64_e32 v[20:21], v[144:145]
	v_lshlrev_b32_e32 v0, 16, v2
	v_mul_f32_e32 v1, 0x3d372713, v0
	v_mul_f32_e32 v1, v1, v0
	v_fma_f32 v1, v1, v0, v0
	v_mul_f32_e32 v1, 0xbfcc422a, v1
	v_mul_f32_e32 v1, 0x3fb8aa3b, v1
	v_exp_f32_e32 v1, v1
	s_nop 0
	v_add_f32_e32 v1, 1.0, v1
	v_rcp_f32_e32 v1, v1
	s_nop 0
	v_fma_f32 v0, v1, v0, -v37
	v_mul_f32_e32 v0, v36, v0
	s_waitcnt vmcnt(0)
	v_fma_f32 v0, v0, v10, v18
	v_cvt_pk_bf16_f32 v0, v0, v17
	ds_write_b16 v39, v0 offset:44336
	v_and_b32_e32 v0, 0xffff0000, v2
	v_mul_f32_e32 v1, 0x3d372713, v0
	v_mul_f32_e32 v1, v1, v0
	v_fma_f32 v1, v1, v0, v0
	v_mul_f32_e32 v1, 0xbfcc422a, v1
	v_mul_f32_e32 v1, 0x3fb8aa3b, v1
	v_exp_f32_e32 v1, v1
	s_nop 0
	v_add_f32_e32 v1, 1.0, v1
	v_rcp_f32_e32 v1, v1
	s_nop 0
	v_fma_f32 v0, v1, v0, -v37
	v_mul_f32_e32 v0, v36, v0
	v_fma_f32 v0, v0, v11, v19
	v_cvt_pk_bf16_f32 v0, v0, v17
	ds_write_b16 v39, v0 offset:44608
	v_lshlrev_b32_e32 v0, 16, v3
	v_mul_f32_e32 v1, 0x3d372713, v0
	v_mul_f32_e32 v1, v1, v0
	v_fma_f32 v1, v1, v0, v0
	v_mul_f32_e32 v1, 0xbfcc422a, v1
	v_mul_f32_e32 v1, 0x3fb8aa3b, v1
	v_exp_f32_e32 v1, v1
	s_nop 0
	v_add_f32_e32 v1, 1.0, v1
	v_rcp_f32_e32 v1, v1
	s_nop 0
	v_fma_f32 v0, v1, v0, -v37
	v_mul_f32_e32 v0, v36, v0
	v_fma_f32 v0, v0, v12, v20
	v_cvt_pk_bf16_f32 v0, v0, v17
	ds_write_b16 v39, v0 offset:44880
	v_and_b32_e32 v0, 0xffff0000, v3
	v_mul_f32_e32 v1, 0x3d372713, v0
	v_mul_f32_e32 v1, v1, v0
	v_fma_f32 v1, v1, v0, v0
	v_mul_f32_e32 v1, 0xbfcc422a, v1
	v_mul_f32_e32 v1, 0x3fb8aa3b, v1
	v_exp_f32_e32 v1, v1
	s_nop 0
	v_add_f32_e32 v1, 1.0, v1
	v_rcp_f32_e32 v1, v1
	s_nop 0
	v_fma_f32 v0, v1, v0, -v37
	v_mul_f32_e32 v0, v36, v0
	v_fmac_f32_e32 v21, v0, v13
	v_cvt_pk_bf16_f32 v0, v21, v17
	ds_write_b16 v39, v0 offset:45152
	v_mov_b64_e32 v[0:1], v[90:91]
	v_mov_b64_e32 v[2:3], v[92:93]
	s_waitcnt lgkmcnt(0)
	v_lshlrev_b32_e32 v10, 16, v0
	v_mul_f32_e32 v11, 0x3d372713, v10
	v_mul_f32_e32 v11, v11, v10
	v_fma_f32 v11, v11, v10, v10
	v_mul_f32_e32 v11, 0xbfcc422a, v11
	v_mul_f32_e32 v11, 0x3fb8aa3b, v11
	v_exp_f32_e32 v11, v11
	v_and_b32_e32 v0, 0xffff0000, v0
	v_add_f32_e32 v11, 1.0, v11
	v_rcp_f32_e32 v11, v11
	s_nop 0
	v_fma_f32 v10, v11, v10, -v37
	v_mul_f32_e32 v14, v36, v10
	v_mov_b64_e32 v[10:11], v[114:115]
	v_mov_b64_e32 v[12:13], v[116:117]
	v_mov_b64_e32 v[18:19], v[146:147]
	v_mov_b64_e32 v[20:21], v[148:149]
	v_fma_f32 v10, v10, v14, v18
	v_cvt_pk_bf16_f32 v10, v10, v17
	ds_write_b16 v39, v10 offset:51952
	v_mul_f32_e32 v10, 0x3d372713, v0
	v_mul_f32_e32 v10, v10, v0
	v_fma_f32 v10, v10, v0, v0
	v_mul_f32_e32 v10, 0xbfcc422a, v10
	v_mul_f32_e32 v10, 0x3fb8aa3b, v10
	v_exp_f32_e32 v10, v10
	s_nop 0
	v_add_f32_e32 v10, 1.0, v10
	v_rcp_f32_e32 v10, v10
	s_nop 0
	v_fma_f32 v0, v10, v0, -v37
	v_mul_f32_e32 v0, v36, v0
	v_fma_f32 v0, v11, v0, v19
	v_cvt_pk_bf16_f32 v0, v0, v17
	ds_write_b16 v39, v0 offset:52224
	v_lshlrev_b32_e32 v0, 16, v1
	v_mul_f32_e32 v10, 0x3d372713, v0
	v_mul_f32_e32 v10, v10, v0
	v_fma_f32 v10, v10, v0, v0
	v_mul_f32_e32 v10, 0xbfcc422a, v10
	v_mul_f32_e32 v10, 0x3fb8aa3b, v10
	v_exp_f32_e32 v10, v10
	s_nop 0
	v_add_f32_e32 v10, 1.0, v10
	v_rcp_f32_e32 v10, v10
	s_nop 0
	v_fma_f32 v0, v10, v0, -v37
	v_mul_f32_e32 v0, v36, v0
	v_fma_f32 v0, v12, v0, v20
	v_cvt_pk_bf16_f32 v0, v0, v17
	ds_write_b16 v39, v0 offset:52496
	v_and_b32_e32 v0, 0xffff0000, v1
	v_mul_f32_e32 v1, 0x3d372713, v0
	v_mul_f32_e32 v1, v1, v0
	v_fma_f32 v1, v1, v0, v0
	v_mul_f32_e32 v1, 0xbfcc422a, v1
	v_mul_f32_e32 v1, 0x3fb8aa3b, v1
	v_exp_f32_e32 v1, v1
	s_nop 0
	v_add_f32_e32 v1, 1.0, v1
	v_rcp_f32_e32 v1, v1
	s_nop 0
	v_fma_f32 v0, v1, v0, -v37
	v_mul_f32_e32 v0, v36, v0
	v_fmac_f32_e32 v21, v13, v0
	v_cvt_pk_bf16_f32 v0, v21, v17
	ds_write_b16 v39, v0 offset:52768
	v_mov_b64_e32 v[10:11], v[118:119]
	v_mov_b64_e32 v[12:13], v[120:121]
	v_mov_b64_e32 v[18:19], v[150:151]
	v_mov_b64_e32 v[20:21], v[152:153]
	v_lshlrev_b32_e32 v0, 16, v2
	v_mul_f32_e32 v1, 0x3d372713, v0
	v_mul_f32_e32 v1, v1, v0
	v_fma_f32 v1, v1, v0, v0
	v_mul_f32_e32 v1, 0xbfcc422a, v1
	v_mul_f32_e32 v1, 0x3fb8aa3b, v1
	v_exp_f32_e32 v1, v1
	s_nop 0
	v_add_f32_e32 v1, 1.0, v1
	v_rcp_f32_e32 v1, v1
	s_nop 0
	v_fma_f32 v0, v1, v0, -v37
	v_mul_f32_e32 v0, v36, v0
	s_waitcnt vmcnt(0)
	v_fma_f32 v0, v0, v10, v18
	v_cvt_pk_bf16_f32 v0, v0, v17
	ds_write_b16 v39, v0 offset:53040
	v_and_b32_e32 v0, 0xffff0000, v2
	v_mul_f32_e32 v1, 0x3d372713, v0
	v_mul_f32_e32 v1, v1, v0
	v_fma_f32 v1, v1, v0, v0
	v_mul_f32_e32 v1, 0xbfcc422a, v1
	v_mul_f32_e32 v1, 0x3fb8aa3b, v1
	v_exp_f32_e32 v1, v1
	s_nop 0
	v_add_f32_e32 v1, 1.0, v1
	v_rcp_f32_e32 v1, v1
	s_nop 0
	v_fma_f32 v0, v1, v0, -v37
	v_mul_f32_e32 v0, v36, v0
	v_fma_f32 v0, v0, v11, v19
	v_cvt_pk_bf16_f32 v0, v0, v17
	ds_write_b16 v39, v0 offset:53312
	v_lshlrev_b32_e32 v0, 16, v3
	v_mul_f32_e32 v1, 0x3d372713, v0
	v_mul_f32_e32 v1, v1, v0
	v_fma_f32 v1, v1, v0, v0
	v_mul_f32_e32 v1, 0xbfcc422a, v1
	v_mul_f32_e32 v1, 0x3fb8aa3b, v1
	v_exp_f32_e32 v1, v1
	s_nop 0
	v_add_f32_e32 v1, 1.0, v1
	v_rcp_f32_e32 v1, v1
	s_nop 0
	v_fma_f32 v0, v1, v0, -v37
	v_mul_f32_e32 v0, v36, v0
	v_fma_f32 v0, v0, v12, v20
	v_cvt_pk_bf16_f32 v0, v0, v17
	ds_write_b16 v39, v0 offset:53584
	v_and_b32_e32 v0, 0xffff0000, v3
	v_mul_f32_e32 v1, 0x3d372713, v0
	v_mul_f32_e32 v1, v1, v0
	v_fma_f32 v1, v1, v0, v0
	v_mul_f32_e32 v1, 0xbfcc422a, v1
	v_mul_f32_e32 v1, 0x3fb8aa3b, v1
	v_exp_f32_e32 v1, v1
	s_nop 0
	v_add_f32_e32 v1, 1.0, v1
	v_rcp_f32_e32 v1, v1
	s_nop 0
	v_fma_f32 v0, v1, v0, -v37
	v_mul_f32_e32 v0, v36, v0
	v_fmac_f32_e32 v21, v0, v13
	v_cvt_pk_bf16_f32 v0, v21, v17
	ds_write_b16 v39, v0 offset:53856
	v_mov_b64_e32 v[0:1], v[94:95]
	v_mov_b64_e32 v[2:3], v[96:97]
	v_mov_b64_e32 v[10:11], v[122:123]
	v_mov_b64_e32 v[12:13], v[124:125]
	v_mov_b64_e32 v[18:19], v[154:155]
	v_mov_b64_e32 v[20:21], v[156:157]
	s_waitcnt lgkmcnt(0)
	v_lshlrev_b32_e32 v6, 16, v0
	v_mul_f32_e32 v7, 0x3d372713, v6
	v_mul_f32_e32 v7, v7, v6
	v_fma_f32 v7, v7, v6, v6
	v_mul_f32_e32 v7, 0xbfcc422a, v7
	v_mul_f32_e32 v7, 0x3fb8aa3b, v7
	v_exp_f32_e32 v7, v7
	v_and_b32_e32 v0, 0xffff0000, v0
	v_add_f32_e32 v7, 1.0, v7
	v_rcp_f32_e32 v7, v7
	s_nop 0
	v_fma_f32 v6, v7, v6, -v37
	v_mul_f32_e32 v6, v36, v6
	v_fma_f32 v6, v10, v6, v18
	v_cvt_pk_bf16_f32 v6, v6, v17
	ds_write_b16 v39, v6 offset:60656
	v_mul_f32_e32 v6, 0x3d372713, v0
	v_mul_f32_e32 v6, v6, v0
	v_fma_f32 v6, v6, v0, v0
	v_mul_f32_e32 v6, 0xbfcc422a, v6
	v_mul_f32_e32 v6, 0x3fb8aa3b, v6
	v_exp_f32_e32 v6, v6
	s_nop 0
	v_add_f32_e32 v6, 1.0, v6
	v_rcp_f32_e32 v6, v6
	s_nop 0
	v_fma_f32 v0, v6, v0, -v37
	v_mul_f32_e32 v0, v36, v0
	v_fma_f32 v0, v11, v0, v19
	v_cvt_pk_bf16_f32 v0, v0, v17
	ds_write_b16 v39, v0 offset:60928
	v_lshlrev_b32_e32 v0, 16, v1
	v_mul_f32_e32 v6, 0x3d372713, v0
	v_mul_f32_e32 v6, v6, v0
	v_fma_f32 v6, v6, v0, v0
	v_mul_f32_e32 v6, 0xbfcc422a, v6
	v_mul_f32_e32 v6, 0x3fb8aa3b, v6
	v_exp_f32_e32 v6, v6
	s_nop 0
	v_add_f32_e32 v6, 1.0, v6
	v_rcp_f32_e32 v6, v6
	s_nop 0
	v_fma_f32 v0, v6, v0, -v37
	v_mul_f32_e32 v0, v36, v0
	v_fma_f32 v0, v12, v0, v20
	v_cvt_pk_bf16_f32 v0, v0, v17
	ds_write_b16 v39, v0 offset:61200
	v_and_b32_e32 v0, 0xffff0000, v1
	v_mul_f32_e32 v1, 0x3d372713, v0
	v_mul_f32_e32 v1, v1, v0
	v_fma_f32 v1, v1, v0, v0
	v_mul_f32_e32 v1, 0xbfcc422a, v1
	v_mul_f32_e32 v1, 0x3fb8aa3b, v1
	v_exp_f32_e32 v1, v1
	s_nop 0
	v_add_f32_e32 v1, 1.0, v1
	v_rcp_f32_e32 v1, v1
	s_nop 0
	v_fma_f32 v0, v1, v0, -v37
	v_mul_f32_e32 v0, v36, v0
	v_fmac_f32_e32 v21, v13, v0
	v_cvt_pk_bf16_f32 v0, v21, v17
	ds_write_b16 v39, v0 offset:61472
	v_mov_b64_e32 v[4:5], v[126:127]
	v_mov_b64_e32 v[6:7], v[128:129]
	s_nop 0
	v_mov_b64_e32 v[8:9], v[158:159]
	v_mov_b64_e32 v[10:11], v[160:161]
	v_lshlrev_b32_e32 v0, 16, v2
	v_mul_f32_e32 v1, 0x3d372713, v0
	v_mul_f32_e32 v1, v1, v0
	v_fma_f32 v1, v1, v0, v0
	v_mul_f32_e32 v1, 0xbfcc422a, v1
	v_mul_f32_e32 v1, 0x3fb8aa3b, v1
	v_exp_f32_e32 v1, v1
	s_nop 0
	v_add_f32_e32 v1, 1.0, v1
	v_rcp_f32_e32 v1, v1
	s_nop 0
	v_fma_f32 v0, v1, v0, -v37
	v_mul_f32_e32 v0, v36, v0
	s_waitcnt vmcnt(0)
	v_fma_f32 v0, v0, v4, v8
	v_cvt_pk_bf16_f32 v0, v0, v17
	ds_write_b16 v39, v0 offset:61744
	v_and_b32_e32 v0, 0xffff0000, v2
	v_mul_f32_e32 v1, 0x3d372713, v0
	v_mul_f32_e32 v1, v1, v0
	v_fma_f32 v1, v1, v0, v0
	v_mul_f32_e32 v1, 0xbfcc422a, v1
	v_mul_f32_e32 v1, 0x3fb8aa3b, v1
	v_exp_f32_e32 v1, v1
	s_nop 0
	v_add_f32_e32 v1, 1.0, v1
	v_rcp_f32_e32 v1, v1
	s_nop 0
	v_fma_f32 v0, v1, v0, -v37
	v_mul_f32_e32 v0, v36, v0
	v_fma_f32 v0, v0, v5, v9
	v_cvt_pk_bf16_f32 v0, v0, v17
	ds_write_b16 v39, v0 offset:62016
	v_lshlrev_b32_e32 v0, 16, v3
	v_mul_f32_e32 v1, 0x3d372713, v0
	v_mul_f32_e32 v1, v1, v0
	v_fma_f32 v1, v1, v0, v0
	v_mul_f32_e32 v1, 0xbfcc422a, v1
	v_mul_f32_e32 v1, 0x3fb8aa3b, v1
	v_exp_f32_e32 v1, v1
	s_nop 0
	v_add_f32_e32 v1, 1.0, v1
	v_rcp_f32_e32 v1, v1
	s_nop 0
	v_fma_f32 v0, v1, v0, -v37
	v_mul_f32_e32 v0, v36, v0
	v_fma_f32 v0, v0, v6, v10
	v_cvt_pk_bf16_f32 v0, v0, v17
	ds_write_b16 v39, v0 offset:62288
	v_and_b32_e32 v0, 0xffff0000, v3
	v_mul_f32_e32 v1, 0x3d372713, v0
	v_mul_f32_e32 v1, v1, v0
	v_fma_f32 v1, v1, v0, v0
	v_mul_f32_e32 v1, 0xbfcc422a, v1
	v_mul_f32_e32 v1, 0x3fb8aa3b, v1
	v_exp_f32_e32 v1, v1
	s_nop 0
	v_add_f32_e32 v1, 1.0, v1
	v_rcp_f32_e32 v1, v1
	s_nop 0
	v_fma_f32 v0, v1, v0, -v37
	v_mul_f32_e32 v0, v36, v0
	v_fmac_f32_e32 v11, v0, v7
	v_cvt_pk_bf16_f32 v0, v11, v17
	ds_write_b16 v39, v0 offset:62560
	s_mov_b32 s4, 0
	s_ashr_i32 s5, s4, 31
	s_lshl_b64 s[4:5], s[4:5], 3
	s_add_u32 s4, s0, s4
	s_addc_u32 s5, s1, s5
	s_waitcnt lgkmcnt(0)
	v_lshl_add_u64 v[4:5], s[4:5], 0, v[42:43]
	v_mov_b64_e32 v[0:1], v[162:163]
	v_mov_b64_e32 v[2:3], v[164:165]
	v_lshl_add_u64 v[42:43], v[42:43], 0, s[14:15]
	v_cndmask_b32_e64 v2, v2, 0, s[40:41]
	v_cndmask_b32_e64 v3, v3, 0, s[40:41]
	v_cndmask_b32_e64 v0, v0, 0, s[40:41]
	v_cndmask_b32_e64 v1, v1, 0, s[40:41]
	v_cvt_pk_bf16_f32 v6, v0, v1
	v_cvt_pk_bf16_f32 v7, v2, v3
	v_mov_b64_e32 v[0:1], v[166:167]
	v_mov_b64_e32 v[2:3], v[168:169]
	v_cndmask_b32_e64 v0, v0, 0, s[40:41]
	v_cndmask_b32_e64 v1, v1, 0, s[40:41]
	v_cndmask_b32_e64 v2, v2, 0, s[40:41]
	v_cndmask_b32_e64 v3, v3, 0, s[40:41]
	v_cvt_pk_bf16_f32 v0, v0, v1
	v_cvt_pk_bf16_f32 v1, v2, v3
	ds_write2_b64 v56, v[6:7], v[0:1] offset1:1
	v_mov_b64_e32 v[0:1], v[170:171]
	v_mov_b64_e32 v[2:3], v[172:173]
	v_cndmask_b32_e64 v2, v2, 0, s[40:41]
	v_cndmask_b32_e64 v3, v3, 0, s[40:41]
	v_cndmask_b32_e64 v0, v0, 0, s[40:41]
	v_cndmask_b32_e64 v1, v1, 0, s[40:41]
	v_cvt_pk_bf16_f32 v6, v0, v1
	v_cvt_pk_bf16_f32 v7, v2, v3
	v_mov_b64_e32 v[0:1], v[174:175]
	v_mov_b64_e32 v[2:3], v[176:177]
	v_cndmask_b32_e64 v0, v0, 0, s[40:41]
	v_cndmask_b32_e64 v1, v1, 0, s[40:41]
	v_cndmask_b32_e64 v2, v2, 0, s[40:41]
	v_cndmask_b32_e64 v3, v3, 0, s[40:41]
	v_cvt_pk_bf16_f32 v0, v0, v1
	v_cvt_pk_bf16_f32 v1, v2, v3
	ds_write2_b64 v56, v[6:7], v[0:1] offset0:2 offset1:3
	v_mov_b64_e32 v[0:1], v[178:179]
	v_mov_b64_e32 v[2:3], v[180:181]
	v_cndmask_b32_e64 v2, v2, 0, s[40:41]
	v_cndmask_b32_e64 v3, v3, 0, s[40:41]
	v_cndmask_b32_e64 v0, v0, 0, s[40:41]
	v_cndmask_b32_e64 v1, v1, 0, s[40:41]
	v_cvt_pk_bf16_f32 v6, v0, v1
	v_cvt_pk_bf16_f32 v7, v2, v3
	v_mov_b64_e32 v[0:1], v[182:183]
	v_mov_b64_e32 v[2:3], v[184:185]
	v_cndmask_b32_e64 v0, v0, 0, s[40:41]
	v_cndmask_b32_e64 v1, v1, 0, s[40:41]
	v_cndmask_b32_e64 v2, v2, 0, s[40:41]
	v_cndmask_b32_e64 v3, v3, 0, s[40:41]
	v_cvt_pk_bf16_f32 v0, v0, v1
	v_cvt_pk_bf16_f32 v1, v2, v3
	ds_write2_b64 v56, v[6:7], v[0:1] offset0:4 offset1:5
	v_mov_b64_e32 v[0:1], v[186:187]
	v_mov_b64_e32 v[2:3], v[188:189]
	v_cndmask_b32_e64 v2, v2, 0, s[40:41]
	v_cndmask_b32_e64 v3, v3, 0, s[40:41]
	v_cndmask_b32_e64 v0, v0, 0, s[40:41]
	v_cndmask_b32_e64 v1, v1, 0, s[40:41]
	v_cvt_pk_bf16_f32 v6, v0, v1
	v_cvt_pk_bf16_f32 v7, v2, v3
	v_mov_b64_e32 v[0:1], v[190:191]
	v_mov_b64_e32 v[2:3], v[192:193]
	v_cndmask_b32_e64 v0, v0, 0, s[40:41]
	v_cndmask_b32_e64 v1, v1, 0, s[40:41]
	v_cndmask_b32_e64 v2, v2, 0, s[40:41]
	v_cndmask_b32_e64 v3, v3, 0, s[40:41]
	v_cvt_pk_bf16_f32 v0, v0, v1
	v_cvt_pk_bf16_f32 v1, v2, v3
	ds_write2_b64 v56, v[6:7], v[0:1] offset0:6 offset1:7
	s_waitcnt lgkmcnt(0)
	s_barrier
	ds_read_b128 v[0:3], v38
	ds_read_b128 v[4:7], v57 offset:34816
	ds_read_b128 v[8:11], v57 offset:39168
	ds_read_b128 v[12:15], v57 offset:43520
	ds_read_b128 v[18:21], v57 offset:47872
	ds_read_b128 v[22:25], v57 offset:52224
	ds_read_b128 v[26:29], v57 offset:56576
	ds_read_b128 v[30:33], v57 offset:60928
	ds_read_b128 v[50:53], v57 offset:65280
	s_waitcnt lgkmcnt(7)
	v_mfma_f32_16x16x32_bf16 v[4:7], v[4:7], v[0:3], 0
	s_waitcnt lgkmcnt(6)
	v_mfma_f32_16x16x32_bf16 v[8:11], v[8:11], v[0:3], 0
	s_waitcnt lgkmcnt(5)
	v_mfma_f32_16x16x32_bf16 v[12:15], v[12:15], v[0:3], 0
	s_waitcnt lgkmcnt(4)
	v_mfma_f32_16x16x32_bf16 v[18:21], v[18:21], v[0:3], 0
	s_waitcnt lgkmcnt(3)
	v_mfma_f32_16x16x32_bf16 v[22:25], v[22:25], v[0:3], 0
	s_waitcnt lgkmcnt(2)
	v_mfma_f32_16x16x32_bf16 v[26:29], v[26:29], v[0:3], 0
	s_waitcnt lgkmcnt(1)
	v_mfma_f32_16x16x32_bf16 v[30:33], v[30:33], v[0:3], 0
	s_waitcnt lgkmcnt(0)
	v_mfma_f32_16x16x32_bf16 v[0:3], v[50:53], v[0:3], 0
	ds_read_b128 v[50:53], v38 offset:64
	ds_read_b128 v[58:61], v57 offset:34880
	s_waitcnt lgkmcnt(0)
	v_mfma_f32_16x16x32_bf16 v[4:7], v[58:61], v[50:53], v[4:7]
	ds_read_b128 v[58:61], v57 offset:39232
	s_waitcnt lgkmcnt(0)
	v_mfma_f32_16x16x32_bf16 v[8:11], v[58:61], v[50:53], v[8:11]
	ds_read_b128 v[58:61], v57 offset:43584
	s_waitcnt lgkmcnt(0)
	v_mfma_f32_16x16x32_bf16 v[12:15], v[58:61], v[50:53], v[12:15]
	ds_read_b128 v[58:61], v57 offset:47936
	s_waitcnt lgkmcnt(0)
	v_mfma_f32_16x16x32_bf16 v[18:21], v[58:61], v[50:53], v[18:21]
	ds_read_b128 v[58:61], v57 offset:52288
	s_waitcnt lgkmcnt(0)
	v_mfma_f32_16x16x32_bf16 v[22:25], v[58:61], v[50:53], v[22:25]
	ds_read_b128 v[58:61], v57 offset:56640
	s_waitcnt lgkmcnt(0)
	v_mfma_f32_16x16x32_bf16 v[26:29], v[58:61], v[50:53], v[26:29]
	ds_read_b128 v[58:61], v57 offset:60992
	s_waitcnt lgkmcnt(0)
	v_mfma_f32_16x16x32_bf16 v[30:33], v[58:61], v[50:53], v[30:33]
	ds_read_b128 v[58:61], v57 offset:65344
	s_waitcnt lgkmcnt(0)
	v_mfma_f32_16x16x32_bf16 v[0:3], v[58:61], v[50:53], v[0:3]
	ds_read_b128 v[50:53], v38 offset:128
	ds_read_b128 v[58:61], v57 offset:34944
	s_waitcnt lgkmcnt(0)
	v_mfma_f32_16x16x32_bf16 v[4:7], v[58:61], v[50:53], v[4:7]
	ds_read_b128 v[58:61], v57 offset:39296
	s_waitcnt lgkmcnt(0)
	v_mfma_f32_16x16x32_bf16 v[8:11], v[58:61], v[50:53], v[8:11]
	ds_read_b128 v[58:61], v57 offset:43648
	s_waitcnt lgkmcnt(0)
	v_mfma_f32_16x16x32_bf16 v[12:15], v[58:61], v[50:53], v[12:15]
	ds_read_b128 v[58:61], v57 offset:48000
	s_waitcnt lgkmcnt(0)
	v_mfma_f32_16x16x32_bf16 v[18:21], v[58:61], v[50:53], v[18:21]
	ds_read_b128 v[58:61], v57 offset:52352
	s_waitcnt lgkmcnt(0)
	v_mfma_f32_16x16x32_bf16 v[58:61], v[58:61], v[50:53], v[22:25]
	s_nop 2
	ds_read_b128 v[22:25], v57 offset:56704
	s_waitcnt lgkmcnt(0)
	v_mfma_f32_16x16x32_bf16 v[62:65], v[22:25], v[50:53], v[26:29]
	ds_read_b128 v[22:25], v57 offset:61056
	s_waitcnt lgkmcnt(0)
	v_mfma_f32_16x16x32_bf16 v[66:69], v[22:25], v[50:53], v[30:33]
	ds_read_b128 v[22:25], v57 offset:65408
	s_waitcnt lgkmcnt(0)
	v_mfma_f32_16x16x32_bf16 v[0:3], v[22:25], v[50:53], v[0:3]
	ds_read_b128 v[50:53], v38 offset:192
	ds_read_b128 v[22:25], v57 offset:35008
	s_waitcnt lgkmcnt(0)
	v_mfma_f32_16x16x32_bf16 v[30:33], v[22:25], v[50:53], v[4:7]
	s_nop 2
	ds_read_b128 v[4:7], v57 offset:39360
	s_waitcnt lgkmcnt(0)
	v_mfma_f32_16x16x32_bf16 v[26:29], v[4:7], v[50:53], v[8:11]
	ds_read_b128 v[4:7], v57 offset:43712
	s_waitcnt lgkmcnt(0)
	v_mfma_f32_16x16x32_bf16 v[22:25], v[4:7], v[50:53], v[12:15]
	ds_read_b128 v[4:7], v57 offset:48064
	s_waitcnt lgkmcnt(0)
	v_mfma_f32_16x16x32_bf16 v[18:21], v[4:7], v[50:53], v[18:21]
	ds_read_b128 v[4:7], v57 offset:52416
	s_waitcnt lgkmcnt(0)
	v_mfma_f32_16x16x32_bf16 v[12:15], v[4:7], v[50:53], v[58:61]
	ds_read_b128 v[4:7], v57 offset:56768
	s_nop 1
	ds_read_b128 v[58:61], v57 offset:65472
	s_waitcnt lgkmcnt(1)
	v_mfma_f32_16x16x32_bf16 v[8:11], v[4:7], v[50:53], v[62:65]
	ds_read_b128 v[4:7], v57 offset:61120
	s_mov_b32 s4, 0
	s_ashr_i32 s5, s4, 31
	s_lshl_b64 s[4:5], s[4:5], 3
	s_add_u32 s4, s0, s4
	s_addc_u32 s5, s1, s5
	s_waitcnt lgkmcnt(0)
	v_mfma_f32_16x16x32_bf16 v[4:7], v[4:7], v[50:53], v[66:69]
	v_mfma_f32_16x16x32_bf16 v[0:3], v[58:61], v[50:53], v[0:3]
	v_lshl_add_u64 v[50:51], s[4:5], 0, v[44:45]
	v_lshl_add_u64 v[50:51], v[50:51], 0, s[42:43]
	v_mov_b32_e32 v58, v224
	v_lshl_add_u64 v[50:51], s[90:91], 0, v[48:49]
	v_add_co_u32_e32 v50, vcc, s86, v50
	v_lshl_add_u64 v[52:53], s[90:91], 0, v[46:47]
	s_nop 0
	v_addc_co_u32_e32 v51, vcc, 0, v51, vcc
	v_mov_b64_e32 v[54:55], v[208:209]
	s_add_u32 s42, s42, 0x200
	s_addc_u32 s43, s43, 0
	s_add_u32 s90, s90, 0x100
	s_addc_u32 s91, s91, 0
	s_cmpk_eq_i32 s42, 0x800
	v_add_f32_e32 v30, v30, v58
	v_add_f32_e32 v31, v31, v58
	v_add_f32_e32 v26, v26, v58
	v_add_f32_e32 v27, v27, v58
	v_add_f32_e32 v22, v22, v58
	v_add_f32_e32 v23, v23, v58
	v_add_f32_e32 v18, v18, v58
	s_waitcnt lgkmcnt(0)
	v_lshlrev_b32_e32 v59, 16, v54
	v_mul_f32_e32 v60, 0x3d372713, v59
	v_mul_f32_e32 v60, v60, v59
	v_fma_f32 v60, v60, v59, v59
	v_mul_f32_e32 v60, 0xbfcc422a, v60
	v_mul_f32_e32 v60, 0x3fb8aa3b, v60
	v_exp_f32_e32 v60, v60
	v_and_b32_e32 v54, 0xffff0000, v54
	v_add_f32_e32 v19, v19, v58
	v_add_f32_e32 v12, v12, v58
	v_add_f32_e32 v60, 1.0, v60
	v_rcp_f32_e32 v60, v60
	v_add_f32_e32 v13, v13, v58
	v_add_f32_e32 v8, v8, v58
	v_add_f32_e32 v9, v9, v58
	v_mul_f32_e32 v59, v60, v59
	v_mul_f32_e32 v30, v30, v59
	v_mul_f32_e32 v59, 0x3d372713, v54
	v_mul_f32_e32 v59, v59, v54
	v_fma_f32 v59, v59, v54, v54
	v_mul_f32_e32 v59, 0xbfcc422a, v59
	v_mul_f32_e32 v59, 0x3fb8aa3b, v59
	v_exp_f32_e32 v59, v59
	v_add_f32_e32 v4, v4, v58
	v_add_f32_e32 v5, v5, v58
	v_add_f32_e32 v0, v0, v58
	v_add_f32_e32 v59, 1.0, v59
	v_rcp_f32_e32 v59, v59
	v_add_f32_e32 v1, v1, v58
	v_mul_f32_e32 v54, v59, v54
	v_mul_f32_e32 v31, v31, v54
	v_cvt_pk_bf16_f32 v54, v30, v31
	v_lshlrev_b32_e32 v31, 16, v55
	v_add_f32_e32 v30, v32, v58
	v_mul_f32_e32 v32, 0x3d372713, v31
	v_mul_f32_e32 v32, v32, v31
	v_fma_f32 v32, v32, v31, v31
	v_mul_f32_e32 v32, 0xbfcc422a, v32
	v_mul_f32_e32 v32, 0x3fb8aa3b, v32
	v_exp_f32_e32 v32, v32
	s_nop 0
	v_add_f32_e32 v32, 1.0, v32
	v_rcp_f32_e32 v32, v32
	s_nop 0
	v_mul_f32_e32 v31, v32, v31
	v_and_b32_e32 v32, 0xffff0000, v55
	v_mul_f32_e32 v30, v30, v31
	v_add_f32_e32 v31, v33, v58
	v_mul_f32_e32 v33, 0x3d372713, v32
	v_mul_f32_e32 v33, v33, v32
	v_fma_f32 v33, v33, v32, v32
	v_mul_f32_e32 v33, 0xbfcc422a, v33
	v_mul_f32_e32 v33, 0x3fb8aa3b, v33
	v_exp_f32_e32 v33, v33
	s_nop 0
	v_add_f32_e32 v33, 1.0, v33
	v_rcp_f32_e32 v33, v33
	s_nop 0
	v_mul_f32_e32 v32, v33, v32
	v_mul_f32_e32 v31, v31, v32
	v_cvt_pk_bf16_f32 v55, v30, v31
	v_add_co_u32_e32 v30, vcc, s2, v52
	s_nop 1
	v_addc_co_u32_e32 v31, vcc, 0, v53, vcc
	global_store_dwordx2 v[30:31], v[54:55], off
	v_mov_b64_e32 v[32:33], v[210:211]
	s_waitcnt lgkmcnt(0)
	v_lshlrev_b32_e32 v52, 16, v32
	v_mul_f32_e32 v53, 0x3d372713, v52
	v_mul_f32_e32 v53, v53, v52
	v_fma_f32 v53, v53, v52, v52
	v_mul_f32_e32 v53, 0xbfcc422a, v53
	v_mul_f32_e32 v53, 0x3fb8aa3b, v53
	v_exp_f32_e32 v53, v53
	v_and_b32_e32 v32, 0xffff0000, v32
	v_add_f32_e32 v53, 1.0, v53
	v_rcp_f32_e32 v53, v53
	s_nop 0
	v_mul_f32_e32 v52, v53, v52
	v_mul_f32_e32 v26, v26, v52
	v_mul_f32_e32 v52, 0x3d372713, v32
	v_mul_f32_e32 v52, v52, v32
	v_fma_f32 v52, v52, v32, v32
	v_mul_f32_e32 v52, 0xbfcc422a, v52
	v_mul_f32_e32 v52, 0x3fb8aa3b, v52
	v_exp_f32_e32 v52, v52
	s_nop 0
	v_add_f32_e32 v52, 1.0, v52
	v_rcp_f32_e32 v52, v52
	s_nop 0
	v_mul_f32_e32 v32, v52, v32
	v_mul_f32_e32 v27, v27, v32
	v_cvt_pk_bf16_f32 v26, v26, v27
	v_add_f32_e32 v27, v28, v58
	v_lshlrev_b32_e32 v28, 16, v33
	v_mul_f32_e32 v32, 0x3d372713, v28
	v_mul_f32_e32 v32, v32, v28
	v_fma_f32 v32, v32, v28, v28
	v_mul_f32_e32 v32, 0xbfcc422a, v32
	v_mul_f32_e32 v32, 0x3fb8aa3b, v32
	v_exp_f32_e32 v32, v32
	s_nop 0
	v_add_f32_e32 v32, 1.0, v32
	v_rcp_f32_e32 v32, v32
	s_nop 0
	v_mul_f32_e32 v28, v32, v28
	v_mul_f32_e32 v27, v27, v28
	v_add_f32_e32 v28, v29, v58
	v_and_b32_e32 v29, 0xffff0000, v33
	v_mul_f32_e32 v32, 0x3d372713, v29
	v_mul_f32_e32 v32, v32, v29
	v_fma_f32 v32, v32, v29, v29
	v_mul_f32_e32 v32, 0xbfcc422a, v32
	v_mul_f32_e32 v32, 0x3fb8aa3b, v32
	v_exp_f32_e32 v32, v32
	s_nop 0
	v_add_f32_e32 v32, 1.0, v32
	v_rcp_f32_e32 v32, v32
	s_nop 0
	v_mul_f32_e32 v29, v32, v29
	v_mul_f32_e32 v28, v28, v29
	v_cvt_pk_bf16_f32 v27, v27, v28
	global_store_dwordx2 v[30:31], v[26:27], off offset:32
	v_mov_b64_e32 v[26:27], v[212:213]
	s_waitcnt lgkmcnt(0)
	v_lshlrev_b32_e32 v28, 16, v26
	v_mul_f32_e32 v29, 0x3d372713, v28
	v_mul_f32_e32 v29, v29, v28
	v_fma_f32 v29, v29, v28, v28
	v_mul_f32_e32 v29, 0xbfcc422a, v29
	v_mul_f32_e32 v29, 0x3fb8aa3b, v29
	v_exp_f32_e32 v29, v29
	v_and_b32_e32 v26, 0xffff0000, v26
	v_add_f32_e32 v29, 1.0, v29
	v_rcp_f32_e32 v29, v29
	s_nop 0
	v_mul_f32_e32 v28, v29, v28
	v_mul_f32_e32 v22, v22, v28
	v_mul_f32_e32 v28, 0x3d372713, v26
	v_mul_f32_e32 v28, v28, v26
	v_fma_f32 v28, v28, v26, v26
	v_mul_f32_e32 v28, 0xbfcc422a, v28
	v_mul_f32_e32 v28, 0x3fb8aa3b, v28
	v_exp_f32_e32 v28, v28
	s_nop 0
	v_add_f32_e32 v28, 1.0, v28
	v_rcp_f32_e32 v28, v28
	s_nop 0
	v_mul_f32_e32 v26, v28, v26
	v_mul_f32_e32 v23, v23, v26
	v_cvt_pk_bf16_f32 v22, v22, v23
	v_add_f32_e32 v23, v24, v58
	v_lshlrev_b32_e32 v24, 16, v27
	v_mul_f32_e32 v26, 0x3d372713, v24
	v_mul_f32_e32 v26, v26, v24
	v_fma_f32 v26, v26, v24, v24
	v_mul_f32_e32 v26, 0xbfcc422a, v26
	v_mul_f32_e32 v26, 0x3fb8aa3b, v26
	v_exp_f32_e32 v26, v26
	s_nop 0
	v_add_f32_e32 v26, 1.0, v26
	v_rcp_f32_e32 v26, v26
	s_nop 0
	v_mul_f32_e32 v24, v26, v24
	v_mul_f32_e32 v23, v23, v24
	v_add_f32_e32 v24, v25, v58
	v_and_b32_e32 v25, 0xffff0000, v27
	v_mul_f32_e32 v26, 0x3d372713, v25
	v_mul_f32_e32 v26, v26, v25
	v_fma_f32 v26, v26, v25, v25
	v_mul_f32_e32 v26, 0xbfcc422a, v26
	v_mul_f32_e32 v26, 0x3fb8aa3b, v26
	v_exp_f32_e32 v26, v26
	s_nop 0
	v_add_f32_e32 v26, 1.0, v26
	v_rcp_f32_e32 v26, v26
	s_nop 0
	v_mul_f32_e32 v25, v26, v25
	v_mul_f32_e32 v24, v24, v25
	v_cvt_pk_bf16_f32 v23, v23, v24
	global_store_dwordx2 v[30:31], v[22:23], off offset:64
	v_mov_b64_e32 v[22:23], v[214:215]
	s_waitcnt lgkmcnt(0)
	v_lshlrev_b32_e32 v24, 16, v22
	v_mul_f32_e32 v25, 0x3d372713, v24
	v_mul_f32_e32 v25, v25, v24
	v_fma_f32 v25, v25, v24, v24
	v_mul_f32_e32 v25, 0xbfcc422a, v25
	v_mul_f32_e32 v25, 0x3fb8aa3b, v25
	v_exp_f32_e32 v25, v25
	v_and_b32_e32 v22, 0xffff0000, v22
	v_add_f32_e32 v25, 1.0, v25
	v_rcp_f32_e32 v25, v25
	s_nop 0
	v_mul_f32_e32 v24, v25, v24
	v_mul_f32_e32 v18, v18, v24
	v_mul_f32_e32 v24, 0x3d372713, v22
	v_mul_f32_e32 v24, v24, v22
	v_fma_f32 v24, v24, v22, v22
	v_mul_f32_e32 v24, 0xbfcc422a, v24
	v_mul_f32_e32 v24, 0x3fb8aa3b, v24
	v_exp_f32_e32 v24, v24
	s_nop 0
	v_add_f32_e32 v24, 1.0, v24
	v_rcp_f32_e32 v24, v24
	s_nop 0
	v_mul_f32_e32 v22, v24, v22
	v_mul_f32_e32 v19, v19, v22
	v_cvt_pk_bf16_f32 v18, v18, v19
	v_add_f32_e32 v19, v20, v58
	v_lshlrev_b32_e32 v20, 16, v23
	v_mul_f32_e32 v22, 0x3d372713, v20
	v_mul_f32_e32 v22, v22, v20
	v_fma_f32 v22, v22, v20, v20
	v_mul_f32_e32 v22, 0xbfcc422a, v22
	v_mul_f32_e32 v22, 0x3fb8aa3b, v22
	v_exp_f32_e32 v22, v22
	s_nop 0
	v_add_f32_e32 v22, 1.0, v22
	v_rcp_f32_e32 v22, v22
	s_nop 0
	v_mul_f32_e32 v20, v22, v20
	v_mul_f32_e32 v19, v19, v20
	v_add_f32_e32 v20, v21, v58
	v_and_b32_e32 v21, 0xffff0000, v23
	v_mul_f32_e32 v22, 0x3d372713, v21
	v_mul_f32_e32 v22, v22, v21
	v_fma_f32 v22, v22, v21, v21
	v_mul_f32_e32 v22, 0xbfcc422a, v22
	v_mul_f32_e32 v22, 0x3fb8aa3b, v22
	v_exp_f32_e32 v22, v22
	s_nop 0
	v_add_f32_e32 v22, 1.0, v22
	v_rcp_f32_e32 v22, v22
	s_nop 0
	v_mul_f32_e32 v21, v22, v21
	v_mul_f32_e32 v20, v20, v21
	v_cvt_pk_bf16_f32 v19, v19, v20
	global_store_dwordx2 v[30:31], v[18:19], off offset:96
	v_mov_b64_e32 v[18:19], v[216:217]
	s_waitcnt lgkmcnt(0)
	v_lshlrev_b32_e32 v20, 16, v18
	v_mul_f32_e32 v21, 0x3d372713, v20
	v_mul_f32_e32 v21, v21, v20
	v_fma_f32 v21, v21, v20, v20
	v_mul_f32_e32 v21, 0xbfcc422a, v21
	v_mul_f32_e32 v21, 0x3fb8aa3b, v21
	v_exp_f32_e32 v21, v21
	v_and_b32_e32 v18, 0xffff0000, v18
	v_add_f32_e32 v21, 1.0, v21
	v_rcp_f32_e32 v21, v21
	s_nop 0
	v_mul_f32_e32 v20, v21, v20
	v_mul_f32_e32 v12, v12, v20
	v_mul_f32_e32 v20, 0x3d372713, v18
	v_mul_f32_e32 v20, v20, v18
	v_fma_f32 v20, v20, v18, v18
	v_mul_f32_e32 v20, 0xbfcc422a, v20
	v_mul_f32_e32 v20, 0x3fb8aa3b, v20
	v_exp_f32_e32 v20, v20
	s_nop 0
	v_add_f32_e32 v20, 1.0, v20
	v_rcp_f32_e32 v20, v20
	s_nop 0
	v_mul_f32_e32 v18, v20, v18
	v_mul_f32_e32 v13, v13, v18
	v_cvt_pk_bf16_f32 v12, v12, v13
	v_add_f32_e32 v13, v14, v58
	v_lshlrev_b32_e32 v14, 16, v19
	v_mul_f32_e32 v18, 0x3d372713, v14
	v_mul_f32_e32 v18, v18, v14
	v_fma_f32 v18, v18, v14, v14
	v_mul_f32_e32 v18, 0xbfcc422a, v18
	v_mul_f32_e32 v18, 0x3fb8aa3b, v18
	v_exp_f32_e32 v18, v18
	s_nop 0
	v_add_f32_e32 v18, 1.0, v18
	v_rcp_f32_e32 v18, v18
	s_nop 0
	v_mul_f32_e32 v14, v18, v14
	v_mul_f32_e32 v13, v13, v14
	v_add_f32_e32 v14, v15, v58
	v_and_b32_e32 v15, 0xffff0000, v19
	v_mul_f32_e32 v18, 0x3d372713, v15
	v_mul_f32_e32 v18, v18, v15
	v_fma_f32 v18, v18, v15, v15
	v_mul_f32_e32 v18, 0xbfcc422a, v18
	v_mul_f32_e32 v18, 0x3fb8aa3b, v18
	v_exp_f32_e32 v18, v18
	s_nop 0
	v_add_f32_e32 v18, 1.0, v18
	v_rcp_f32_e32 v18, v18
	s_nop 0
	v_mul_f32_e32 v15, v18, v15
	v_mul_f32_e32 v14, v14, v15
	v_cvt_pk_bf16_f32 v13, v13, v14
	global_store_dwordx2 v[30:31], v[12:13], off offset:128
	v_mov_b64_e32 v[12:13], v[218:219]
	s_waitcnt lgkmcnt(0)
	v_lshlrev_b32_e32 v14, 16, v12
	v_mul_f32_e32 v15, 0x3d372713, v14
	v_mul_f32_e32 v15, v15, v14
	v_fma_f32 v15, v15, v14, v14
	v_mul_f32_e32 v15, 0xbfcc422a, v15
	v_mul_f32_e32 v15, 0x3fb8aa3b, v15
	v_exp_f32_e32 v15, v15
	v_and_b32_e32 v12, 0xffff0000, v12
	v_add_f32_e32 v15, 1.0, v15
	v_rcp_f32_e32 v15, v15
	s_nop 0
	v_mul_f32_e32 v14, v15, v14
	v_mul_f32_e32 v8, v8, v14
	v_mul_f32_e32 v14, 0x3d372713, v12
	v_mul_f32_e32 v14, v14, v12
	v_fma_f32 v14, v14, v12, v12
	v_mul_f32_e32 v14, 0xbfcc422a, v14
	v_mul_f32_e32 v14, 0x3fb8aa3b, v14
	v_exp_f32_e32 v14, v14
	s_nop 0
	v_add_f32_e32 v14, 1.0, v14
	v_rcp_f32_e32 v14, v14
	s_nop 0
	v_mul_f32_e32 v12, v14, v12
	v_mul_f32_e32 v9, v9, v12
	v_cvt_pk_bf16_f32 v8, v8, v9
	v_add_f32_e32 v9, v10, v58
	v_lshlrev_b32_e32 v10, 16, v13
	v_mul_f32_e32 v12, 0x3d372713, v10
	v_mul_f32_e32 v12, v12, v10
	v_fma_f32 v12, v12, v10, v10
	v_mul_f32_e32 v12, 0xbfcc422a, v12
	v_mul_f32_e32 v12, 0x3fb8aa3b, v12
	v_exp_f32_e32 v12, v12
	s_nop 0
	v_add_f32_e32 v12, 1.0, v12
	v_rcp_f32_e32 v12, v12
	s_nop 0
	v_mul_f32_e32 v10, v12, v10
	v_mul_f32_e32 v9, v9, v10
	v_add_f32_e32 v10, v11, v58
	v_and_b32_e32 v11, 0xffff0000, v13
	v_mul_f32_e32 v12, 0x3d372713, v11
	v_mul_f32_e32 v12, v12, v11
	v_fma_f32 v12, v12, v11, v11
	v_mul_f32_e32 v12, 0xbfcc422a, v12
	v_mul_f32_e32 v12, 0x3fb8aa3b, v12
	v_exp_f32_e32 v12, v12
	s_nop 0
	v_add_f32_e32 v12, 1.0, v12
	v_rcp_f32_e32 v12, v12
	s_nop 0
	v_mul_f32_e32 v11, v12, v11
	v_mul_f32_e32 v10, v10, v11
	v_cvt_pk_bf16_f32 v9, v9, v10
	global_store_dwordx2 v[30:31], v[8:9], off offset:160
	v_mov_b64_e32 v[8:9], v[220:221]
	s_waitcnt lgkmcnt(0)
	v_lshlrev_b32_e32 v10, 16, v8
	v_mul_f32_e32 v11, 0x3d372713, v10
	v_mul_f32_e32 v11, v11, v10
	v_fma_f32 v11, v11, v10, v10
	v_mul_f32_e32 v11, 0xbfcc422a, v11
	v_mul_f32_e32 v11, 0x3fb8aa3b, v11
	v_exp_f32_e32 v11, v11
	v_and_b32_e32 v8, 0xffff0000, v8
	v_add_f32_e32 v11, 1.0, v11
	v_rcp_f32_e32 v11, v11
	s_nop 0
	v_mul_f32_e32 v10, v11, v10
	v_mul_f32_e32 v4, v4, v10
	v_mul_f32_e32 v10, 0x3d372713, v8
	v_mul_f32_e32 v10, v10, v8
	v_fma_f32 v10, v10, v8, v8
	v_mul_f32_e32 v10, 0xbfcc422a, v10
	v_mul_f32_e32 v10, 0x3fb8aa3b, v10
	v_exp_f32_e32 v10, v10
	s_nop 0
	v_add_f32_e32 v10, 1.0, v10
	v_rcp_f32_e32 v10, v10
	s_nop 0
	v_mul_f32_e32 v8, v10, v8
	v_mul_f32_e32 v5, v5, v8
	v_cvt_pk_bf16_f32 v4, v4, v5
	v_add_f32_e32 v5, v6, v58
	v_lshlrev_b32_e32 v6, 16, v9
	v_mul_f32_e32 v8, 0x3d372713, v6
	v_mul_f32_e32 v8, v8, v6
	v_fma_f32 v8, v8, v6, v6
	v_mul_f32_e32 v8, 0xbfcc422a, v8
	v_mul_f32_e32 v8, 0x3fb8aa3b, v8
	v_exp_f32_e32 v8, v8
	s_nop 0
	v_add_f32_e32 v8, 1.0, v8
	v_rcp_f32_e32 v8, v8
	s_nop 0
	v_mul_f32_e32 v6, v8, v6
	v_mul_f32_e32 v5, v5, v6
	v_add_f32_e32 v6, v7, v58
	v_and_b32_e32 v7, 0xffff0000, v9
	v_mul_f32_e32 v8, 0x3d372713, v7
	v_mul_f32_e32 v8, v8, v7
	v_fma_f32 v8, v8, v7, v7
	v_mul_f32_e32 v8, 0xbfcc422a, v8
	v_mul_f32_e32 v8, 0x3fb8aa3b, v8
	v_exp_f32_e32 v8, v8
	s_nop 0
	v_add_f32_e32 v8, 1.0, v8
	v_rcp_f32_e32 v8, v8
	s_nop 0
	v_mul_f32_e32 v7, v8, v7
	v_mul_f32_e32 v6, v6, v7
	v_cvt_pk_bf16_f32 v5, v5, v6
	global_store_dwordx2 v[30:31], v[4:5], off offset:192
	v_mov_b64_e32 v[4:5], v[222:223]
	s_waitcnt lgkmcnt(0)
	v_lshlrev_b32_e32 v6, 16, v4
	v_mul_f32_e32 v7, 0x3d372713, v6
	v_mul_f32_e32 v7, v7, v6
	v_fma_f32 v7, v7, v6, v6
	v_mul_f32_e32 v7, 0xbfcc422a, v7
	v_mul_f32_e32 v7, 0x3fb8aa3b, v7
	v_exp_f32_e32 v7, v7
	v_and_b32_e32 v4, 0xffff0000, v4
	v_add_f32_e32 v7, 1.0, v7
	v_rcp_f32_e32 v7, v7
	s_nop 0
	v_mul_f32_e32 v6, v7, v6
	v_mul_f32_e32 v0, v0, v6
	v_mul_f32_e32 v6, 0x3d372713, v4
	v_mul_f32_e32 v6, v6, v4
	v_fma_f32 v6, v6, v4, v4
	v_mul_f32_e32 v6, 0xbfcc422a, v6
	v_mul_f32_e32 v6, 0x3fb8aa3b, v6
	v_exp_f32_e32 v6, v6
	s_nop 0
	v_add_f32_e32 v6, 1.0, v6
	v_rcp_f32_e32 v6, v6
	s_nop 0
	v_mul_f32_e32 v4, v6, v4
	v_mul_f32_e32 v1, v1, v4
	v_cvt_pk_bf16_f32 v0, v0, v1
	v_add_f32_e32 v1, v2, v58
	v_lshlrev_b32_e32 v2, 16, v5
	v_mul_f32_e32 v4, 0x3d372713, v2
	v_mul_f32_e32 v4, v4, v2
	v_fma_f32 v4, v4, v2, v2
	v_mul_f32_e32 v4, 0xbfcc422a, v4
	v_mul_f32_e32 v4, 0x3fb8aa3b, v4
	v_exp_f32_e32 v4, v4
	s_nop 0
	v_add_f32_e32 v4, 1.0, v4
	v_rcp_f32_e32 v4, v4
	s_nop 0
	v_mul_f32_e32 v2, v4, v2
	v_mul_f32_e32 v1, v1, v2
	v_add_f32_e32 v2, v3, v58
	v_and_b32_e32 v3, 0xffff0000, v5
	v_mul_f32_e32 v4, 0x3d372713, v3
	v_mul_f32_e32 v4, v4, v3
	v_fma_f32 v4, v4, v3, v3
	v_mul_f32_e32 v4, 0xbfcc422a, v4
	v_mul_f32_e32 v4, 0x3fb8aa3b, v4
	v_exp_f32_e32 v4, v4
	s_nop 0
	v_add_f32_e32 v4, 1.0, v4
	v_rcp_f32_e32 v4, v4
	s_nop 0
	v_mul_f32_e32 v3, v4, v3
	v_mul_f32_e32 v2, v2, v3
	v_cvt_pk_bf16_f32 v1, v1, v2
	global_store_dwordx2 v[30:31], v[0:1], off offset:224
	s_waitcnt lgkmcnt(0)
	s_barrier
	s_cbranch_scc0 .LBB0_680

.LBB0_682:
	v_mov_b32_e32 v72, v228
	v_readlane_b32 s4, v255, 23
	v_ashrrev_i32_e32 v68, 6, v72
	v_and_b32_e32 v71, 15, v72
	v_lshl_or_b32 v58, v68, 7, v71
	v_ashrrev_i32_e32 v59, 31, v58
	v_lshlrev_b64 v[0:1], 7, v[58:59]
	v_or_b32_e32 v8, 16, v58
	v_or_b32_e32 v18, 32, v58
	v_or_b32_e32 v26, 48, v58
	v_or_b32_e32 v34, 64, v58
	v_or_b32_e32 v42, 0x50, v58
	v_or_b32_e32 v50, 0x60, v58
	v_or_b32_e32 v58, 0x70, v58
	v_and_b32_e32 v16, 48, v72
	v_readlane_b32 s5, v255, 24
	v_ashrrev_i32_e32 v9, 31, v8
	v_ashrrev_i32_e32 v19, 31, v18
	v_ashrrev_i32_e32 v27, 31, v26
	v_ashrrev_i32_e32 v35, 31, v34
	v_ashrrev_i32_e32 v43, 31, v42
	v_ashrrev_i32_e32 v51, 31, v50
	v_ashrrev_i32_e32 v59, 31, v58
	v_lshl_add_u64 v[60:61], s[4:5], 0, v[16:17]
	v_lshlrev_b64 v[8:9], 7, v[8:9]
	v_lshlrev_b64 v[18:19], 7, v[18:19]
	v_lshlrev_b64 v[26:27], 7, v[26:27]
	v_lshlrev_b64 v[34:35], 7, v[34:35]
	v_lshlrev_b64 v[42:43], 7, v[42:43]
	v_lshlrev_b64 v[50:51], 7, v[50:51]
	v_lshlrev_b64 v[58:59], 7, v[58:59]
	v_lshl_add_u64 v[4:5], v[60:61], 0, v[0:1]
	v_lshl_add_u64 v[12:13], v[60:61], 0, v[8:9]
	v_lshl_add_u64 v[22:23], v[60:61], 0, v[18:19]
	v_lshl_add_u64 v[30:31], v[60:61], 0, v[26:27]
	v_lshl_add_u64 v[38:39], v[60:61], 0, v[34:35]
	v_lshl_add_u64 v[46:47], v[60:61], 0, v[42:43]
	v_lshl_add_u64 v[54:55], v[60:61], 0, v[50:51]
	v_lshl_add_u64 v[62:63], v[60:61], 0, v[58:59]
	global_load_dwordx4 v[0:3], v[4:5], off
	s_nop 0
	global_load_dwordx4 v[4:7], v[4:5], off offset:64
	s_nop 0
	global_load_dwordx4 v[8:11], v[12:13], off
	s_nop 0
	global_load_dwordx4 v[12:15], v[12:13], off offset:64
	s_nop 0
	global_load_dwordx4 v[18:21], v[22:23], off
	s_nop 0
	global_load_dwordx4 v[22:25], v[22:23], off offset:64
	s_nop 0
	global_load_dwordx4 v[26:29], v[30:31], off
	s_nop 0
	global_load_dwordx4 v[30:33], v[30:31], off offset:64
	s_nop 0
	global_load_dwordx4 v[34:37], v[38:39], off
	s_nop 0
	global_load_dwordx4 v[38:41], v[38:39], off offset:64
	s_nop 0
	global_load_dwordx4 v[42:45], v[46:47], off
	s_nop 0
	global_load_dwordx4 v[46:49], v[46:47], off offset:64
	s_nop 0
	global_load_dwordx4 v[50:53], v[54:55], off
	s_nop 0
	global_load_dwordx4 v[54:57], v[54:55], off offset:64
	s_nop 0
	global_load_dwordx4 v[58:61], v[62:63], off
	s_nop 0
	global_load_dwordx4 v[62:65], v[62:63], off offset:64
	s_mov_b32 s8, 0
	s_ashr_i32 s9, s8, 31
	s_lshl_b32 s4, s28, 6
	s_lshl_b64 s[8:9], s[8:9], 3
	s_add_u32 s8, s0, s8
	s_addc_u32 s9, s1, s9
	s_load_dwordx2 s[8:9], s[8:9], 0x58
	v_readlane_b32 s14, v255, 35
	v_readlane_b32 s15, v255, 36
	v_ashrrev_i32_e32 v73, 31, v72
	s_mul_i32 s2, s28, 0x118000
	s_waitcnt lgkmcnt(0)
	s_add_u32 s8, s8, s14
	s_addc_u32 s9, s9, s15
	v_lshl_add_u64 v[66:67], v[72:73], 2, s[8:9]
	v_add_co_u32_e32 v74, vcc, s68, v66
	v_readlane_b32 s14, v255, 30
	s_nop 0
	v_addc_co_u32_e32 v75, vcc, 0, v67, vcc
	global_load_dword v16, v[66:67], off
	global_load_dword v79, v[66:67], off offset:2048
	global_load_dword v80, v[74:75], off
	global_load_dword v81, v[74:75], off offset:2048
	s_mov_b32 s8, 0
	s_ashr_i32 s9, s8, 31
	s_lshl_b64 s[8:9], s[8:9], 3
	s_add_u32 s8, s0, s8
	s_addc_u32 s9, s1, s9
	s_load_dwordx2 s[8:9], s[8:9], 0x60
	v_add_u32_e32 v66, s14, v72
	v_ashrrev_i32_e32 v67, 31, v66
	v_lshlrev_b64 v[66:67], 2, v[66:67]
	s_mul_hi_i32 s5, s4, 0x4600
	s_waitcnt lgkmcnt(0)
	v_lshl_add_u64 v[74:75], s[8:9], 0, v[66:67]
	global_load_dword v82, v[74:75], off
	s_mov_b32 s8, 0
	s_ashr_i32 s9, s8, 31
	s_lshl_b64 s[8:9], s[8:9], 3
	s_add_u32 s8, s0, s8
	s_addc_u32 s9, s1, s9
	s_load_dwordx2 s[8:9], s[8:9], 0x70
	v_readlane_b32 s15, v255, 31
	s_waitcnt lgkmcnt(0)
	v_lshl_add_u64 v[74:75], s[8:9], 0, v[66:67]
	global_load_dword v83, v[74:75], off
	s_mov_b32 s8, 0
	s_ashr_i32 s9, s8, 31
	s_lshl_b64 s[8:9], s[8:9], 3
	s_add_u32 s8, s0, s8
	s_addc_u32 s9, s1, s9
	s_load_dwordx2 s[8:9], s[8:9], 0x80
	s_waitcnt lgkmcnt(0)
	v_lshl_add_u64 v[74:75], s[8:9], 0, v[66:67]
	global_load_dword v84, v[74:75], off
	s_mov_b32 s8, 0
	s_ashr_i32 s9, s8, 31
	s_lshl_b64 s[8:9], s[8:9], 3
	s_add_u32 s8, s0, s8
	s_addc_u32 s9, s1, s9
	s_load_dwordx2 s[8:9], s[8:9], 0x88
	s_waitcnt lgkmcnt(0)
	v_lshl_add_u64 v[66:67], s[8:9], 0, v[66:67]
	global_load_dword v69, v[66:67], off
	s_add_u32 s8, s94, s2
	s_addc_u32 s9, s95, s5
	v_lshl_add_u64 v[66:67], v[72:73], 1, s[8:9]
	s_add_u32 s100, s8, 0x800
	s_addc_u32 s101, s9, 0
	v_lshlrev_b32_e32 v138, 1, v228
	v_add_u32_e32 v139, 0x4600, v138
	v_add_u32_e32 v140, 0x8c00, v138
	v_add_u32_e32 v141, 0xd200, v138
	v_add_u32_e32 v142, 0x11800, v138
	v_add_u32_e32 v143, 0x15e00, v138
	v_add_u32_e32 v144, 0x1a400, v138
	v_add_u32_e32 v145, 0x1ea00, v138
	v_add_u32_e32 v146, 0x23000, v138
	v_add_u32_e32 v147, 0x27600, v138
	v_add_u32_e32 v148, 0x2bc00, v138
	v_add_u32_e32 v149, 0x30200, v138
	v_add_u32_e32 v150, 0x34800, v138
	v_add_u32_e32 v151, 0x38e00, v138
	v_add_u32_e32 v152, 0x3d400, v138
	v_add_u32_e32 v153, 0x41a00, v138
	global_load_ushort v154, v138, s[100:101]
	global_load_ushort v155, v139, s[100:101]
	global_load_ushort v156, v140, s[100:101]
	global_load_ushort v157, v141, s[100:101]
	global_load_ushort v158, v142, s[100:101]
	global_load_ushort v159, v143, s[100:101]
	global_load_ushort v160, v144, s[100:101]
	global_load_ushort v161, v145, s[100:101]
	global_load_ushort v162, v146, s[100:101]
	global_load_ushort v163, v147, s[100:101]
	global_load_ushort v164, v148, s[100:101]
	global_load_ushort v165, v149, s[100:101]
	global_load_ushort v166, v150, s[100:101]
	global_load_ushort v167, v151, s[100:101]
	global_load_ushort v168, v152, s[100:101]
	global_load_ushort v169, v153, s[100:101]
	global_load_ushort v170, v138, s[100:101] offset:1024
	global_load_ushort v171, v139, s[100:101] offset:1024
	global_load_ushort v172, v140, s[100:101] offset:1024
	global_load_ushort v173, v141, s[100:101] offset:1024
	global_load_ushort v174, v142, s[100:101] offset:1024
	global_load_ushort v175, v143, s[100:101] offset:1024
	global_load_ushort v176, v144, s[100:101] offset:1024
	global_load_ushort v177, v145, s[100:101] offset:1024
	global_load_ushort v178, v146, s[100:101] offset:1024
	global_load_ushort v179, v147, s[100:101] offset:1024
	global_load_ushort v180, v148, s[100:101] offset:1024
	global_load_ushort v181, v149, s[100:101] offset:1024
	global_load_ushort v182, v150, s[100:101] offset:1024
	global_load_ushort v183, v151, s[100:101] offset:1024
	global_load_ushort v184, v152, s[100:101] offset:1024
	global_load_ushort v185, v153, s[100:101] offset:1024
	v_add_u32_e32 v212, 0x0, v138
	v_add_u32_e32 v213, 0x1000, v138
	v_add_u32_e32 v214, 0x2000, v138
	v_add_u32_e32 v215, 0x3000, v138
	s_and_b32 s2, s4, 0x80000fc0
	s_mov_b64 s[8:9], 0x800
	s_cmp_lt_i32 s2, 1
	v_lshl_add_u64 v[66:67], v[66:67], 0, s[8:9]
	s_cbranch_scc1 .LBB0_684
	v_add_co_u32_e32 v74, vcc, 0xffff7400, v66
	s_nop 1
	v_addc_co_u32_e32 v75, vcc, -1, v67, vcc
	global_load_ushort v91, v[74:75], off
	v_add_co_u32_e32 v74, vcc, 0xffff2e00, v66
	s_nop 1
	v_addc_co_u32_e32 v75, vcc, -1, v67, vcc
	global_load_ushort v90, v[74:75], off
	v_add_co_u32_e32 v74, vcc, 0xffffba00, v66
	s_nop 1
	v_addc_co_u32_e32 v75, vcc, -1, v67, vcc
	global_load_ushort v92, v[74:75], off
	s_waitcnt vmcnt(0) lgkmcnt(0)
	v_lshlrev_b32_e32 v91, 16, v91
	v_lshlrev_b32_e32 v90, 16, v90
	v_lshlrev_b32_e32 v92, 16, v92
	s_branch .LBB0_685

.LBB0_760:
	s_lshr_b32 s2, s13, 2
	s_and_b32 s37, s13, 3
	v_mov_b32_e32 v106, v228
	s_bfe_u32 s8, s13, 0x60002
	s_lshl_b32 s5, s2, 6
	s_lshl_b32 s4, s37, 7
	s_cmp_lg_u32 s8, 0
	v_ashrrev_i32_e32 v104, 3, v106
	s_cselect_b64 s[8:9], -1, 0
	v_cmp_lt_i32_e32 vcc, 2, v104
	s_waitcnt vmcnt(0)
	v_add_u32_e32 v0, -3, v104
	s_or_b64 vcc, s[8:9], vcc
	v_cndmask_b32_e32 v0, 0, v0, vcc
	v_cndmask_b32_e64 v44, 0, 1.0, vcc
	v_cmp_lt_i32_e32 vcc, 1, v104
	v_add_u32_e32 v4, -2, v104
	s_or_b64 vcc, s[8:9], vcc
	v_cndmask_b32_e32 v4, 0, v4, vcc
	v_cndmask_b32_e64 v42, 0, 1.0, vcc
	v_cmp_lt_i32_e32 vcc, 0, v104
	v_add_u32_e32 v8, -1, v104
	s_or_b64 vcc, s[8:9], vcc
	v_cndmask_b32_e32 v8, 0, v8, vcc
	v_cndmask_b32_e64 v40, 0, 1.0, vcc
	v_cmp_lt_i32_e32 vcc, -1, v104
	s_movk_i32 s2, 0x110
	s_or_b64 vcc, s[8:9], vcc
	v_and_b32_e32 v105, 7, v106
	v_mul_lo_u32 v109, v104, s2
	s_movk_i32 s2, 0x410
	v_cndmask_b32_e32 v14, 0, v104, vcc
	v_lshlrev_b32_e32 v108, 4, v105
	v_mul_lo_u32 v1, v104, s2
	v_add_u32_e32 v0, s5, v0
	v_mov_b64_e32 v[12:13], s[94:95]
	v_add_u32_e32 v4, s5, v4
	v_add_u32_e32 v8, s5, v8
	v_add_u32_e32 v14, s5, v14
	v_add_u32_e32 v107, 0, v1
	v_or_b32_e32 v39, s4, v108
	v_mad_i64_i32 v[0:1], s[38:39], v0, s66, v[12:13]
	v_mad_i64_i32 v[4:5], s[38:39], v4, s66, v[12:13]
	v_mad_i64_i32 v[8:9], s[38:39], v8, s66, v[12:13]
	v_mad_i64_i32 v[12:13], s[8:9], v14, s66, v[12:13]
	v_lshl_add_u64 v[46:47], v[0:1], 0, s[26:27]
	v_lshlrev_b32_e32 v16, 1, v39
	v_lshl_add_u64 v[48:49], v[4:5], 0, s[26:27]
	v_lshl_add_u64 v[50:51], v[8:9], 0, s[26:27]
	v_lshl_add_u64 v[52:53], v[12:13], 0, s[26:27]
	v_lshl_add_u64 v[0:1], v[46:47], 0, v[16:17]
	v_lshl_add_u64 v[4:5], v[48:49], 0, v[16:17]
	v_lshl_add_u64 v[8:9], v[50:51], 0, v[16:17]
	v_lshl_add_u64 v[12:13], v[52:53], 0, v[16:17]
	global_load_dwordx4 v[30:33], v[0:1], off
	s_nop 0
	global_load_dwordx4 v[0:3], v[0:1], off offset:16
	s_nop 0
	global_load_dwordx4 v[26:29], v[4:5], off
	s_nop 0
	global_load_dwordx4 v[4:7], v[4:5], off offset:16
	s_nop 0
	global_load_dwordx4 v[22:25], v[8:9], off
	s_nop 0
	global_load_dwordx4 v[8:11], v[8:9], off offset:16
	s_nop 0
	global_load_dwordx4 v[18:21], v[12:13], off
	s_nop 0
	global_load_dwordx4 v[12:15], v[12:13], off offset:16
	s_mov_b32 s8, 0
	s_ashr_i32 s9, s8, 31
	s_lshl_b64 s[8:9], s[8:9], 3
	s_add_u32 s8, s0, s8
	s_addc_u32 s9, s1, s9
	s_load_dwordx2 s[98:99], s[0:1], 0x98
	s_load_dwordx2 s[100:101], s[0:1], 0xa0
	s_load_dwordx2 s[8:9], s[8:9], 0x90
	v_lshlrev_b32_e32 v41, 2, v39
	v_cndmask_b32_e64 v38, 0, 1.0, vcc
	v_and_b32_e32 v111, 64, v234
	v_or_b32_e32 v16, 0x400, v16
	s_waitcnt lgkmcnt(0)
	v_or_b32_e32 v188, s5, v228
	v_lshlrev_b32_e32 v188, 5, v188
	v_lshl_add_u32 v188, s37, 2, v188
	global_load_dword v189, v188, s[42:43] offset:16
	global_load_dword v190, v188, s[42:43]
	v_mov_b32_e32 v188, s37
	v_or_b32_e32 v188, s35, v188
	v_lshlrev_b32_e32 v188, 2, v188
	global_load_dword v191, v188, s[98:99]
	global_load_dword v192, v188, s[100:101]
	s_add_u32 s98, s8, s16
	s_addc_u32 s99, s9, s17
	s_add_u32 s100, s8, s18
	s_addc_u32 s101, s9, s19
	s_add_u32 s30, s8, s22
	s_addc_u32 s31, s9, s23
	s_add_u32 s8, s8, s15
	s_addc_u32 s9, s9, s14
	global_load_dwordx4 v[34:37], v41, s[8:9] offset:48
	global_load_dwordx4 v[54:57], v41, s[8:9] offset:32
	global_load_dwordx4 v[58:61], v41, s[8:9] offset:16
	global_load_dwordx4 v[62:65], v41, s[8:9]
	global_load_dwordx4 v[140:143], v41, s[98:99] offset:48
	global_load_dwordx4 v[144:147], v41, s[98:99] offset:32
	global_load_dwordx4 v[148:151], v41, s[98:99] offset:16
	global_load_dwordx4 v[152:155], v41, s[98:99]
	global_load_dwordx4 v[156:159], v41, s[100:101] offset:48
	global_load_dwordx4 v[160:163], v41, s[100:101] offset:32
	global_load_dwordx4 v[164:167], v41, s[100:101] offset:16
	global_load_dwordx4 v[168:171], v41, s[100:101]
	global_load_dwordx4 v[172:175], v41, s[30:31] offset:48
	global_load_dwordx4 v[176:179], v41, s[30:31] offset:32
	global_load_dwordx4 v[180:183], v41, s[30:31] offset:16
	global_load_dwordx4 v[184:187], v41, s[30:31]
	s_mov_b32 s8, 0
	s_ashr_i32 s9, s8, 31
	s_lshl_b64 s[8:9], s[8:9], 3
	s_add_u32 s8, s0, s8
	s_addc_u32 s9, s1, s9
	v_lshl_add_u32 v110, v105, 6, v107
	s_waitcnt lgkmcnt(0)
	s_add_u32 s8, s8, s16
	s_addc_u32 s9, s9, s17
	s_waitcnt vmcnt(0)
	v_lshlrev_b32_e32 v43, 16, v30
	v_and_b32_e32 v30, 0xffff0000, v30
	v_lshlrev_b32_e32 v84, 16, v18
	v_and_b32_e32 v18, 0xffff0000, v18
	v_pk_mul_f32 v[58:59], v[44:45], v[58:59] op_sel_hi:[0,1]
	v_pk_mul_f32 v[62:63], v[44:45], v[62:63] op_sel_hi:[0,1]
	v_pk_mul_f32 v[64:65], v[44:45], v[64:65] op_sel_hi:[0,1]
	v_fma_f32 v82, v63, v30, 0
	v_lshlrev_b32_e32 v30, 16, v31
	v_fma_f32 v83, v62, v43, 0
	v_fma_f32 v81, v64, v30, 0
	v_and_b32_e32 v30, 0xffff0000, v31
	v_lshlrev_b32_e32 v43, 16, v32
	v_and_b32_e32 v32, 0xffff0000, v32
	v_fma_f32 v80, v65, v30, 0
	v_pk_mul_f32 v[30:31], v[44:45], v[60:61] op_sel_hi:[0,1]
	v_fma_f32 v78, v59, v32, 0
	v_lshlrev_b32_e32 v32, 16, v33
	v_fma_f32 v45, v30, v32, 0
	v_and_b32_e32 v30, 0xffff0000, v33
	v_fma_f32 v79, v58, v43, 0
	v_fma_f32 v43, v31, v30, 0
	v_pk_mul_f32 v[58:59], v[44:45], v[56:57] op_sel_hi:[0,1]
	v_pk_mul_f32 v[62:63], v[44:45], v[54:55] op_sel_hi:[0,1]
	v_pk_mul_f32 v[54:55], v[44:45], v[36:37] op_sel_hi:[0,1]
	v_pk_mul_f32 v[56:57], v[44:45], v[34:35] op_sel_hi:[0,1]
	v_mov_b64_e32 v[30:31], v[140:141]
	v_mov_b64_e32 v[32:33], v[142:143]
	v_mov_b64_e32 v[34:35], v[144:145]
	v_mov_b64_e32 v[36:37], v[146:147]
	v_mov_b64_e32 v[64:65], v[148:149]
	v_mov_b64_e32 v[66:67], v[150:151]
	v_mov_b64_e32 v[68:69], v[152:153]
	v_mov_b64_e32 v[70:71], v[154:155]
	s_mov_b32 s8, 0
	s_ashr_i32 s9, s8, 31
	s_lshl_b64 s[8:9], s[8:9], 3
	s_add_u32 s8, s0, s8
	s_addc_u32 s9, s1, s9
	s_waitcnt lgkmcnt(0)
	s_add_u32 s8, s8, s18
	s_addc_u32 s9, s9, s19
	s_waitcnt vmcnt(0)
	v_pk_mul_f32 v[60:61], v[42:43], v[70:71] op_sel_hi:[0,1]
	v_pk_mul_f32 v[68:69], v[42:43], v[68:69] op_sel_hi:[0,1]
	v_lshlrev_b32_e32 v70, 16, v26
	v_and_b32_e32 v26, 0xffff0000, v26
	v_fmac_f32_e32 v82, v69, v26
	v_lshlrev_b32_e32 v26, 16, v27
	v_fmac_f32_e32 v81, v60, v26
	v_and_b32_e32 v26, 0xffff0000, v27
	v_fmac_f32_e32 v80, v61, v26
	v_pk_mul_f32 v[60:61], v[42:43], v[64:65] op_sel_hi:[0,1]
	v_lshlrev_b32_e32 v64, 16, v28
	v_and_b32_e32 v28, 0xffff0000, v28
	v_pk_mul_f32 v[26:27], v[42:43], v[66:67] op_sel_hi:[0,1]
	v_fmac_f32_e32 v78, v61, v28
	v_lshlrev_b32_e32 v28, 16, v29
	v_fmac_f32_e32 v45, v26, v28
	v_and_b32_e32 v26, 0xffff0000, v29
	v_fmac_f32_e32 v43, v27, v26
	v_fmac_f32_e32 v83, v68, v70
	v_fmac_f32_e32 v79, v60, v64
	v_pk_mul_f32 v[66:67], v[42:43], v[36:37] op_sel_hi:[0,1]
	v_pk_mul_f32 v[70:71], v[42:43], v[34:35] op_sel_hi:[0,1]
	v_pk_mul_f32 v[60:61], v[42:43], v[32:33] op_sel_hi:[0,1]
	v_pk_mul_f32 v[64:65], v[42:43], v[30:31] op_sel_hi:[0,1]
	v_mov_b64_e32 v[26:27], v[156:157]
	v_mov_b64_e32 v[28:29], v[158:159]
	v_mov_b64_e32 v[30:31], v[160:161]
	v_mov_b64_e32 v[32:33], v[162:163]
	v_mov_b64_e32 v[34:35], v[164:165]
	v_mov_b64_e32 v[36:37], v[166:167]
	v_mov_b64_e32 v[72:73], v[168:169]
	v_mov_b64_e32 v[74:75], v[170:171]
	s_mov_b32 s8, 0
	s_ashr_i32 s9, s8, 31
	s_lshl_b64 s[8:9], s[8:9], 3
	s_add_u32 s8, s0, s8
	s_addc_u32 s9, s1, s9
	s_waitcnt lgkmcnt(0)
	s_add_u32 s8, s8, s22
	s_addc_u32 s9, s9, s23
	s_waitcnt vmcnt(2)
	v_pk_mul_f32 v[76:77], v[40:41], v[30:31] op_sel_hi:[0,1]
	s_waitcnt vmcnt(1)
	v_pk_mul_f32 v[34:35], v[40:41], v[34:35] op_sel_hi:[0,1]
	s_waitcnt vmcnt(0)
	v_pk_mul_f32 v[68:69], v[40:41], v[74:75] op_sel_hi:[0,1]
	v_pk_mul_f32 v[72:73], v[40:41], v[72:73] op_sel_hi:[0,1]
	v_lshlrev_b32_e32 v74, 16, v22
	v_and_b32_e32 v22, 0xffff0000, v22
	v_fmac_f32_e32 v82, v73, v22
	v_lshlrev_b32_e32 v22, 16, v23
	v_fmac_f32_e32 v81, v68, v22
	v_and_b32_e32 v22, 0xffff0000, v23
	v_fmac_f32_e32 v80, v69, v22
	v_pk_mul_f32 v[22:23], v[40:41], v[36:37] op_sel_hi:[0,1]
	v_lshlrev_b32_e32 v36, 16, v24
	v_and_b32_e32 v24, 0xffff0000, v24
	v_fmac_f32_e32 v78, v35, v24
	v_lshlrev_b32_e32 v24, 16, v25
	v_fmac_f32_e32 v45, v22, v24
	v_and_b32_e32 v22, 0xffff0000, v25
	v_fmac_f32_e32 v83, v72, v74
	v_fmac_f32_e32 v79, v34, v36
	v_fmac_f32_e32 v43, v23, v22
	v_pk_mul_f32 v[74:75], v[40:41], v[32:33] op_sel_hi:[0,1]
	v_pk_mul_f32 v[68:69], v[40:41], v[28:29] op_sel_hi:[0,1]
	v_pk_mul_f32 v[72:73], v[40:41], v[26:27] op_sel_hi:[0,1]
	v_mov_b64_e32 v[22:23], v[172:173]
	v_mov_b64_e32 v[24:25], v[174:175]
	v_mov_b64_e32 v[26:27], v[176:177]
	v_mov_b64_e32 v[28:29], v[178:179]
	v_mov_b64_e32 v[30:31], v[180:181]
	v_mov_b64_e32 v[32:33], v[182:183]
	v_mov_b64_e32 v[34:35], v[184:185]
	v_mov_b64_e32 v[36:37], v[186:187]
	s_waitcnt vmcnt(2)
	v_pk_mul_f32 v[26:27], v[38:39], v[26:27] op_sel_hi:[0,1]
	s_waitcnt vmcnt(1)
	v_pk_mul_f32 v[30:31], v[38:39], v[30:31] op_sel_hi:[0,1]
	s_waitcnt vmcnt(0)
	v_pk_mul_f32 v[34:35], v[38:39], v[34:35] op_sel_hi:[0,1]
	v_pk_mul_f32 v[36:37], v[38:39], v[36:37] op_sel_hi:[0,1]
	v_fmac_f32_e32 v82, v35, v18
	v_lshlrev_b32_e32 v18, 16, v19
	v_fmac_f32_e32 v81, v36, v18
	v_and_b32_e32 v18, 0xffff0000, v19
	v_fmac_f32_e32 v80, v37, v18
	v_pk_mul_f32 v[18:19], v[38:39], v[32:33] op_sel_hi:[0,1]
	v_lshlrev_b32_e32 v32, 16, v20
	v_and_b32_e32 v20, 0xffff0000, v20
	v_fmac_f32_e32 v83, v34, v84
	v_fmac_f32_e32 v78, v31, v20
	v_lshlrev_b32_e32 v20, 16, v21
	v_fmac_f32_e32 v45, v18, v20
	v_and_b32_e32 v18, 0xffff0000, v21
	v_pk_mul_f32 v[20:21], v[38:39], v[22:23] op_sel_hi:[0,1]
	v_mul_f32_e32 v22, 0xbfb8aa3b, v83
	v_exp_f32_e32 v22, v22
	v_fmac_f32_e32 v79, v30, v32
	v_fmac_f32_e32 v43, v19, v18
	v_and_b32_e32 v23, 0xffff0000, v0
	v_add_f32_e32 v22, 1.0, v22
	v_rcp_f32_e32 v22, v22
	v_pk_mul_f32 v[18:19], v[38:39], v[24:25] op_sel_hi:[0,1]
	v_and_b32_e32 v25, 0xffff0000, v4
	v_lshlrev_b32_e32 v24, 16, v4
	v_mul_f32_e32 v30, v83, v22
	v_mul_f32_e32 v22, 0xbfb8aa3b, v82
	v_exp_f32_e32 v22, v22
	v_lshlrev_b32_e32 v4, 16, v9
	v_pk_mul_f32 v[28:29], v[38:39], v[28:29] op_sel_hi:[0,1]
	v_add_f32_e32 v22, 1.0, v22
	v_rcp_f32_e32 v22, v22
	s_nop 0
	v_mul_f32_e32 v31, v82, v22
	v_mul_f32_e32 v22, 0xbfb8aa3b, v81
	v_exp_f32_e32 v22, v22
	s_nop 0
	v_add_f32_e32 v22, 1.0, v22
	v_rcp_f32_e32 v22, v22
	s_nop 0
	v_mul_f32_e32 v32, v81, v22
	v_mul_f32_e32 v22, 0xbfb8aa3b, v80
	v_exp_f32_e32 v22, v22
	s_nop 0
	v_add_f32_e32 v22, 1.0, v22
	v_rcp_f32_e32 v22, v22
	s_nop 0
	v_mul_f32_e32 v33, v80, v22
	v_mul_f32_e32 v22, 0xbfb8aa3b, v79
	v_exp_f32_e32 v22, v22
	s_nop 0
	v_add_f32_e32 v22, 1.0, v22
	v_rcp_f32_e32 v22, v22
	s_nop 0
	v_mul_f32_e32 v34, v79, v22
	v_mul_f32_e32 v22, 0xbfb8aa3b, v78
	v_exp_f32_e32 v22, v22
	s_nop 0
	v_add_f32_e32 v22, 1.0, v22
	v_rcp_f32_e32 v22, v22
	s_nop 0
	v_mul_f32_e32 v35, v78, v22
	v_mul_f32_e32 v22, 0xbfb8aa3b, v45
	v_exp_f32_e32 v22, v22
	s_nop 0
	v_add_f32_e32 v22, 1.0, v22
	v_rcp_f32_e32 v22, v22
	s_nop 0
	v_mul_f32_e32 v36, v45, v22
	v_mul_f32_e32 v22, 0xbfb8aa3b, v43
	v_exp_f32_e32 v22, v22
	s_nop 0
	v_add_f32_e32 v22, 1.0, v22
	v_rcp_f32_e32 v22, v22
	s_nop 0
	v_mul_f32_e32 v37, v43, v22
	v_lshlrev_b32_e32 v22, 16, v0
	v_pk_fma_f32 v[22:23], v[62:63], v[22:23], 0 op_sel_hi:[1,1,0]
	v_mul_f32_e32 v43, v31, v31
	v_pk_fma_f32 v[22:23], v[70:71], v[24:25], v[22:23]
	v_and_b32_e32 v25, 0xffff0000, v8
	v_lshlrev_b32_e32 v24, 16, v8
	v_pk_fma_f32 v[22:23], v[76:77], v[24:25], v[22:23]
	v_and_b32_e32 v25, 0xffff0000, v12
	v_lshlrev_b32_e32 v24, 16, v12
	v_pk_fma_f32 v[22:23], v[26:27], v[24:25], v[22:23]
	v_fmac_f32_e32 v43, v30, v30
	v_mul_f32_e32 v0, 0xbfb8aa3b, v22
	v_exp_f32_e32 v0, v0
	v_fmac_f32_e32 v43, v32, v32
	v_fmac_f32_e32 v43, v33, v33
	v_fmac_f32_e32 v43, v34, v34
	v_add_f32_e32 v0, 1.0, v0
	v_rcp_f32_e32 v24, v0
	v_mul_f32_e32 v0, 0xbfb8aa3b, v23
	v_exp_f32_e32 v0, v0
	v_fmac_f32_e32 v43, v35, v35
	v_fmac_f32_e32 v43, v36, v36
	v_fmac_f32_e32 v43, v37, v37
	v_add_f32_e32 v0, 1.0, v0
	v_rcp_f32_e32 v25, v0
	s_nop 0
	v_pk_mul_f32 v[22:23], v[22:23], v[24:25]
	s_nop 0
	v_pk_mul_f32 v[24:25], v[22:23], v[22:23]
	s_nop 0
	v_add_f32_e32 v0, v24, v43
	v_add_f32_e32 v8, v25, v0
	v_and_b32_e32 v25, 0xffff0000, v1
	v_lshlrev_b32_e32 v24, 16, v1
	v_pk_fma_f32 v[0:1], v[58:59], v[24:25], 0 op_sel_hi:[1,1,0]
	v_and_b32_e32 v25, 0xffff0000, v5
	v_lshlrev_b32_e32 v24, 16, v5
	v_pk_fma_f32 v[0:1], v[66:67], v[24:25], v[0:1]
	v_and_b32_e32 v5, 0xffff0000, v9
	v_pk_fma_f32 v[0:1], v[74:75], v[4:5], v[0:1]
	v_and_b32_e32 v5, 0xffff0000, v13
	v_lshlrev_b32_e32 v4, 16, v13
	v_pk_fma_f32 v[0:1], v[28:29], v[4:5], v[0:1]
	v_and_b32_e32 v9, 0xffff0000, v6
	v_mul_f32_e32 v4, 0xbfb8aa3b, v0
	v_mul_f32_e32 v5, 0xbfb8aa3b, v1
	v_exp_f32_e32 v4, v4
	v_exp_f32_e32 v5, v5
	v_add_f32_e32 v4, 1.0, v4
	v_add_f32_e32 v5, 1.0, v5
	v_rcp_f32_e32 v4, v4
	v_rcp_f32_e32 v5, v5
	s_nop 0
	v_pk_mul_f32 v[0:1], v[0:1], v[4:5]
	s_nop 0
	v_pk_mul_f32 v[4:5], v[0:1], v[0:1]
	s_nop 0
	v_add_f32_e32 v4, v4, v8
	v_add_f32_e32 v12, v5, v4
	v_and_b32_e32 v5, 0xffff0000, v2
	v_lshlrev_b32_e32 v4, 16, v2
	v_pk_fma_f32 v[4:5], v[56:57], v[4:5], 0 op_sel_hi:[1,1,0]
	v_lshlrev_b32_e32 v8, 16, v6
	v_pk_fma_f32 v[4:5], v[64:65], v[8:9], v[4:5]
	v_and_b32_e32 v9, 0xffff0000, v10
	v_lshlrev_b32_e32 v8, 16, v10
	v_pk_fma_f32 v[4:5], v[72:73], v[8:9], v[4:5]
	v_and_b32_e32 v9, 0xffff0000, v14
	v_lshlrev_b32_e32 v8, 16, v14
	v_pk_fma_f32 v[4:5], v[20:21], v[8:9], v[4:5]
	v_lshlrev_b32_e32 v6, 16, v11
	v_mul_f32_e32 v2, 0xbfb8aa3b, v4
	v_exp_f32_e32 v2, v2
	s_nop 0
	v_add_f32_e32 v2, 1.0, v2
	v_rcp_f32_e32 v8, v2
	v_mul_f32_e32 v2, 0xbfb8aa3b, v5
	v_exp_f32_e32 v2, v2
	s_nop 0
	v_add_f32_e32 v2, 1.0, v2
	v_rcp_f32_e32 v9, v2
	s_nop 0
	v_pk_mul_f32 v[4:5], v[4:5], v[8:9]
	s_nop 0
	v_pk_mul_f32 v[8:9], v[4:5], v[4:5]
	s_nop 0
	v_add_f32_e32 v2, v8, v12
	v_add_f32_e32 v10, v9, v2
	v_and_b32_e32 v9, 0xffff0000, v3
	v_lshlrev_b32_e32 v8, 16, v3
	v_pk_fma_f32 v[2:3], v[54:55], v[8:9], 0 op_sel_hi:[1,1,0]
	v_and_b32_e32 v9, 0xffff0000, v7
	v_lshlrev_b32_e32 v8, 16, v7
	v_pk_fma_f32 v[2:3], v[60:61], v[8:9], v[2:3]
	v_and_b32_e32 v7, 0xffff0000, v11
	v_pk_fma_f32 v[2:3], v[68:69], v[6:7], v[2:3]
	v_and_b32_e32 v7, 0xffff0000, v15
	v_lshlrev_b32_e32 v6, 16, v15
	v_pk_fma_f32 v[2:3], v[18:19], v[6:7], v[2:3]
	v_add_u32_e32 v8, 64, v111
	v_mul_f32_e32 v6, 0xbfb8aa3b, v3
	v_exp_f32_e32 v6, v6
	s_nop 0
	v_add_f32_e32 v6, 1.0, v6
	v_rcp_f32_e32 v7, v6
	v_mul_f32_e32 v6, 0xbfb8aa3b, v2
	v_exp_f32_e32 v6, v6
	s_nop 0
	v_add_f32_e32 v6, 1.0, v6
	v_rcp_f32_e32 v6, v6
	s_nop 0
	v_pk_mul_f32 v[2:3], v[2:3], v[6:7]
	s_nop 0
	v_pk_mul_f32 v[6:7], v[2:3], v[2:3]
	s_nop 0
	v_add_f32_e32 v6, v6, v10
	v_add_f32_e32 v6, v7, v6
	v_xor_b32_e32 v7, 1, v234
	v_cmp_lt_i32_e32 vcc, v7, v8
	s_nop 1
	v_cndmask_b32_e32 v7, v234, v7, vcc
	v_lshlrev_b32_e32 v45, 2, v7
	ds_bpermute_b32 v7, v45, v6
	s_waitcnt lgkmcnt(0)
	v_add_f32_e32 v6, v6, v7
	v_xor_b32_e32 v7, 2, v234
	v_cmp_lt_i32_e32 vcc, v7, v8
	s_nop 1
	v_cndmask_b32_e32 v7, v234, v7, vcc
	v_lshlrev_b32_e32 v112, 2, v7
	ds_bpermute_b32 v7, v112, v6
	s_waitcnt lgkmcnt(0)
	v_add_f32_e32 v6, v6, v7
	v_xor_b32_e32 v7, 4, v234
	v_cmp_lt_i32_e32 vcc, v7, v8
	s_nop 1
	v_cndmask_b32_e32 v7, v234, v7, vcc
	v_lshlrev_b32_e32 v113, 2, v7
	ds_bpermute_b32 v7, v113, v6
	s_waitcnt lgkmcnt(0)
	v_add_f32_e32 v6, v6, v7
	v_add_f32_e32 v6, 0x358637bd, v6
	v_cmp_gt_f32_e32 vcc, s33, v6
	v_mul_f32_e32 v7, 0x4b800000, v6
	s_nop 0
	v_cndmask_b32_e32 v6, v6, v7, vcc
	v_rsq_f32_e32 v6, v6
	s_nop 0
	v_mul_f32_e32 v7, 0x45800000, v6
	v_cndmask_b32_e32 v6, v6, v7, vcc
	v_mul_f32_e32 v6, 0x3db504f3, v6
	v_mul_f32_e32 v7, v30, v6
	v_mul_f32_e32 v8, v31, v6
	v_mul_f32_e32 v9, v32, v6
	v_mul_f32_e32 v10, v33, v6
	v_mul_f32_e32 v11, v34, v6
	v_mul_f32_e32 v12, v35, v6
	v_mul_f32_e32 v13, v36, v6
	v_mul_f32_e32 v14, v37, v6
	v_mul_f32_e32 v15, v22, v6
	v_mul_f32_e32 v18, v23, v6
	v_mul_f32_e32 v0, v0, v6
	v_mul_f32_e32 v1, v1, v6
	v_mul_f32_e32 v4, v4, v6
	v_mul_f32_e32 v5, v5, v6
	v_mul_f32_e32 v2, v2, v6
	v_mul_f32_e32 v3, v3, v6
	v_lshlrev_b32_e32 v6, 5, v105
	v_add3_u32 v43, 0, v6, v109
	v_cvt_pk_bf16_f32 v6, v7, v8
	v_add_u32_e32 v8, 0x4400, v43
	v_cvt_pk_bf16_f32 v7, v9, v10
	ds_write2_b32 v8, v6, v7 offset1:1
	v_cvt_pk_bf16_f32 v6, v11, v12
	v_cvt_pk_bf16_f32 v0, v0, v1
	v_cvt_pk_bf16_f32 v7, v13, v14
	ds_write2_b32 v8, v6, v7 offset0:2 offset1:3
	v_cvt_pk_bf16_f32 v6, v15, v18
	ds_write2_b32 v8, v6, v0 offset0:4 offset1:5
	v_cvt_pk_bf16_f32 v0, v4, v5
	v_cvt_pk_bf16_f32 v1, v2, v3
	ds_write2_b32 v8, v0, v1 offset0:6 offset1:7
	v_lshl_add_u64 v[0:1], v[46:47], 0, v[16:17]
	global_load_dwordx4 v[30:33], v[0:1], off
	global_load_dwordx4 v[12:15], v[0:1], off offset:16
	v_lshl_add_u64 v[0:1], v[48:49], 0, v[16:17]
	global_load_dwordx4 v[26:29], v[0:1], off
	global_load_dwordx4 v[8:11], v[0:1], off offset:16
	v_lshl_add_u64 v[0:1], v[50:51], 0, v[16:17]
	global_load_dwordx4 v[22:25], v[0:1], off
	global_load_dwordx4 v[4:7], v[0:1], off offset:16
	v_lshl_add_u64 v[0:1], v[52:53], 0, v[16:17]
	global_load_dwordx4 v[18:21], v[0:1], off
	s_nop 0
	global_load_dwordx4 v[0:3], v[0:1], off offset:16
	s_mov_b32 s8, 0
	s_ashr_i32 s9, s8, 31
	s_lshl_b64 s[8:9], s[8:9], 3
	s_add_u32 s8, s0, s8
	s_addc_u32 s9, s1, s9
	s_load_dwordx2 s[8:9], s[8:9], 0x90
	s_waitcnt lgkmcnt(0)
	s_add_u32 s98, s8, s16
	s_addc_u32 s99, s9, s17
	s_add_u32 s100, s8, s18
	s_addc_u32 s101, s9, s19
	s_add_u32 s30, s8, s22
	s_addc_u32 s31, s9, s23
	s_add_u32 s8, s8, s15
	s_addc_u32 s9, s9, s14
	global_load_dwordx4 v[58:61], v41, s[8:9] offset:2096
	global_load_dwordx4 v[62:65], v41, s[8:9] offset:2080
	global_load_dwordx4 v[34:37], v41, s[8:9] offset:2064
	global_load_dwordx4 v[54:57], v41, s[8:9] offset:2048
	global_load_dwordx4 v[140:143], v41, s[98:99] offset:2096
	global_load_dwordx4 v[144:147], v41, s[98:99] offset:2080
	global_load_dwordx4 v[148:151], v41, s[98:99] offset:2064
	global_load_dwordx4 v[152:155], v41, s[98:99] offset:2048
	global_load_dwordx4 v[156:159], v41, s[100:101] offset:2096
	global_load_dwordx4 v[160:163], v41, s[100:101] offset:2080
	global_load_dwordx4 v[164:167], v41, s[100:101] offset:2064
	global_load_dwordx4 v[168:171], v41, s[100:101] offset:2048
	global_load_dwordx4 v[172:175], v41, s[30:31] offset:2096
	global_load_dwordx4 v[176:179], v41, s[30:31] offset:2080
	global_load_dwordx4 v[180:183], v41, s[30:31] offset:2064
	global_load_dwordx4 v[184:187], v41, s[30:31] offset:2048
	s_mov_b32 s8, 0
	s_ashr_i32 s9, s8, 31
	s_lshl_b64 s[8:9], s[8:9], 3
	s_add_u32 s8, s0, s8
	s_addc_u32 s9, s1, s9
	s_waitcnt lgkmcnt(0)
	s_add_u32 s8, s8, s16
	s_addc_u32 s9, s9, s17
	s_waitcnt vmcnt(0)
	v_pk_mul_f32 v[92:93], v[44:45], v[60:61] op_sel_hi:[0,1]
	v_pk_mul_f32 v[74:75], v[44:45], v[58:59] op_sel_hi:[0,1]
	v_pk_mul_f32 v[66:67], v[44:45], v[34:35] op_sel_hi:[0,1]
	v_pk_mul_f32 v[78:79], v[44:45], v[54:55] op_sel_hi:[0,1]
	v_pk_mul_f32 v[34:35], v[44:45], v[64:65] op_sel_hi:[0,1]
	v_pk_mul_f32 v[54:55], v[44:45], v[62:63] op_sel_hi:[0,1]
	v_mov_b64_e32 v[82:83], v[140:141]
	v_mov_b64_e32 v[84:85], v[142:143]
	v_mov_b64_e32 v[58:59], v[144:145]
	v_mov_b64_e32 v[60:61], v[146:147]
	v_mov_b64_e32 v[88:89], v[148:149]
	v_mov_b64_e32 v[90:91], v[150:151]
	v_mov_b64_e32 v[62:63], v[152:153]
	v_mov_b64_e32 v[64:65], v[154:155]
	s_mov_b32 s8, 0
	s_ashr_i32 s9, s8, 31
	s_lshl_b64 s[8:9], s[8:9], 3
	s_add_u32 s8, s0, s8
	s_addc_u32 s9, s1, s9
	v_pk_mul_f32 v[70:71], v[44:45], v[56:57] op_sel_hi:[0,1]
	v_pk_mul_f32 v[56:57], v[44:45], v[36:37] op_sel_hi:[0,1]
	s_waitcnt lgkmcnt(0)
	s_add_u32 s8, s8, s18
	s_addc_u32 s9, s9, s19
	v_mov_b64_e32 v[100:101], v[156:157]
	v_mov_b64_e32 v[102:103], v[158:159]
	v_mov_b64_e32 v[114:115], v[160:161]
	v_mov_b64_e32 v[116:117], v[162:163]
	v_mov_b64_e32 v[118:119], v[164:165]
	v_mov_b64_e32 v[120:121], v[166:167]
	v_mov_b64_e32 v[94:95], v[168:169]
	v_mov_b64_e32 v[96:97], v[170:171]
	s_mov_b32 s8, 0
	s_ashr_i32 s9, s8, 31
	s_lshl_b64 s[8:9], s[8:9], 3
	s_add_u32 s8, s0, s8
	s_addc_u32 s9, s1, s9
	s_waitcnt lgkmcnt(0)
	s_add_u32 s8, s8, s22
	s_addc_u32 s9, s9, s23
	s_waitcnt vmcnt(7)
	v_pk_mul_f32 v[98:99], v[42:43], v[84:85] op_sel_hi:[0,1]
	s_waitcnt vmcnt(6)
	v_pk_mul_f32 v[36:37], v[42:43], v[60:61] op_sel_hi:[0,1]
	v_pk_mul_f32 v[60:61], v[42:43], v[58:59] op_sel_hi:[0,1]
	s_waitcnt vmcnt(4)
	v_pk_mul_f32 v[80:81], v[42:43], v[64:65] op_sel_hi:[0,1]
	v_pk_mul_f32 v[84:85], v[42:43], v[82:83] op_sel_hi:[0,1]
	v_pk_mul_f32 v[86:87], v[42:43], v[62:63] op_sel_hi:[0,1]
	v_pk_mul_f32 v[62:63], v[42:43], v[90:91] op_sel_hi:[0,1]
	v_pk_mul_f32 v[72:73], v[42:43], v[88:89] op_sel_hi:[0,1]
	s_waitcnt vmcnt(3)
	v_pk_mul_f32 v[130:131], v[40:41], v[100:101] op_sel_hi:[0,1]
	s_waitcnt vmcnt(2)
	v_pk_mul_f32 v[58:59], v[40:41], v[116:117] op_sel_hi:[0,1]
	s_waitcnt vmcnt(1)
	v_pk_mul_f32 v[68:69], v[40:41], v[120:121] op_sel_hi:[0,1]
	v_pk_mul_f32 v[82:83], v[40:41], v[118:119] op_sel_hi:[0,1]
	v_pk_mul_f32 v[64:65], v[40:41], v[114:115] op_sel_hi:[0,1]
	v_mov_b64_e32 v[114:115], v[172:173]
	v_mov_b64_e32 v[116:117], v[174:175]
	v_mov_b64_e32 v[118:119], v[176:177]
	v_mov_b64_e32 v[120:121], v[178:179]
	v_mov_b64_e32 v[122:123], v[180:181]
	v_mov_b64_e32 v[124:125], v[182:183]
	v_mov_b64_e32 v[126:127], v[184:185]
	v_mov_b64_e32 v[128:129], v[186:187]
	v_pk_mul_f32 v[102:103], v[40:41], v[102:103] op_sel_hi:[0,1]
	s_waitcnt vmcnt(4)
	v_pk_mul_f32 v[88:89], v[40:41], v[96:97] op_sel_hi:[0,1]
	v_pk_mul_f32 v[96:97], v[40:41], v[94:95] op_sel_hi:[0,1]
	s_waitcnt vmcnt(3)
	v_pk_mul_f32 v[114:115], v[38:39], v[114:115] op_sel_hi:[0,1]
	s_waitcnt vmcnt(2)
	v_pk_mul_f32 v[90:91], v[38:39], v[118:119] op_sel_hi:[0,1]
	v_and_b32_e32 v119, 0xffff0000, v14
	v_lshlrev_b32_e32 v118, 16, v14
	v_pk_fma_f32 v[74:75], v[74:75], v[118:119], 0 op_sel_hi:[1,1,0]
	v_and_b32_e32 v119, 0xffff0000, v10
	v_lshlrev_b32_e32 v118, 16, v10
	v_pk_fma_f32 v[74:75], v[84:85], v[118:119], v[74:75]
	v_and_b32_e32 v85, 0xffff0000, v6
	v_lshlrev_b32_e32 v84, 16, v6
	v_pk_fma_f32 v[74:75], v[130:131], v[84:85], v[74:75]
	v_and_b32_e32 v85, 0xffff0000, v2
	v_lshlrev_b32_e32 v84, 16, v2
	v_pk_fma_f32 v[74:75], v[114:115], v[84:85], v[74:75]
	v_and_b32_e32 v115, 0xffff0000, v15
	v_mul_f32_e32 v2, 0xbfb8aa3b, v74
	v_exp_f32_e32 v2, v2
	v_lshlrev_b32_e32 v114, 16, v15
	v_pk_fma_f32 v[14:15], v[92:93], v[114:115], 0 op_sel_hi:[1,1,0]
	v_and_b32_e32 v93, 0xffff0000, v11
	v_add_f32_e32 v2, 1.0, v2
	v_rcp_f32_e32 v84, v2
	v_mul_f32_e32 v2, 0xbfb8aa3b, v75
	v_exp_f32_e32 v2, v2
	v_lshlrev_b32_e32 v92, 16, v11
	v_pk_fma_f32 v[10:11], v[98:99], v[92:93], v[14:15]
	v_and_b32_e32 v15, 0xffff0000, v7
	v_lshlrev_b32_e32 v14, 16, v7
	v_pk_mul_f32 v[116:117], v[38:39], v[116:117] op_sel_hi:[0,1]
	v_add_f32_e32 v2, 1.0, v2
	v_pk_fma_f32 v[6:7], v[102:103], v[14:15], v[10:11]
	v_and_b32_e32 v11, 0xffff0000, v3
	v_lshlrev_b32_e32 v10, 16, v3
	v_rcp_f32_e32 v85, v2
	v_pk_fma_f32 v[2:3], v[116:117], v[10:11], v[6:7]
	v_lshlrev_b32_e32 v10, 16, v30
	v_and_b32_e32 v11, 0xffff0000, v30
	v_lshlrev_b32_e32 v30, 16, v31
	v_and_b32_e32 v31, 0xffff0000, v31
	v_pk_fma_f32 v[10:11], v[78:79], v[10:11], 0 op_sel_hi:[1,1,0]
	v_lshlrev_b32_e32 v14, 16, v26
	v_and_b32_e32 v15, 0xffff0000, v26
	v_pk_fma_f32 v[30:31], v[70:71], v[30:31], 0 op_sel_hi:[1,1,0]
	v_lshlrev_b32_e32 v26, 16, v27
	v_and_b32_e32 v27, 0xffff0000, v27
	v_pk_fma_f32 v[10:11], v[86:87], v[14:15], v[10:11]
	v_lshlrev_b32_e32 v14, 16, v22
	v_and_b32_e32 v15, 0xffff0000, v22
	v_pk_fma_f32 v[26:27], v[80:81], v[26:27], v[30:31]
	v_lshlrev_b32_e32 v22, 16, v23
	v_and_b32_e32 v23, 0xffff0000, v23
	s_waitcnt vmcnt(0)
	v_pk_mul_f32 v[128:129], v[38:39], v[128:129] op_sel_hi:[0,1]
	v_pk_fma_f32 v[10:11], v[96:97], v[14:15], v[10:11]
	v_lshlrev_b32_e32 v14, 16, v18
	v_and_b32_e32 v15, 0xffff0000, v18
	v_pk_fma_f32 v[22:23], v[88:89], v[22:23], v[26:27]
	v_lshlrev_b32_e32 v18, 16, v19
	v_and_b32_e32 v19, 0xffff0000, v19
	v_pk_fma_f32 v[18:19], v[128:129], v[18:19], v[22:23]
	v_lshlrev_b32_e32 v26, 16, v32
	v_mul_f32_e32 v16, 0xbfb8aa3b, v18
	v_exp_f32_e32 v16, v16
	v_and_b32_e32 v27, 0xffff0000, v32
	v_pk_fma_f32 v[26:27], v[66:67], v[26:27], 0 op_sel_hi:[1,1,0]
	v_lshlrev_b32_e32 v30, 16, v28
	v_add_f32_e32 v16, 1.0, v16
	v_rcp_f32_e32 v22, v16
	v_mul_f32_e32 v16, 0xbfb8aa3b, v19
	v_exp_f32_e32 v16, v16
	v_and_b32_e32 v31, 0xffff0000, v28
	v_pk_fma_f32 v[26:27], v[72:73], v[30:31], v[26:27]
	v_lshlrev_b32_e32 v30, 16, v24
	v_and_b32_e32 v31, 0xffff0000, v24
	v_pk_mul_f32 v[100:101], v[38:39], v[122:123] op_sel_hi:[0,1]
	v_pk_fma_f32 v[26:27], v[82:83], v[30:31], v[26:27]
	v_lshlrev_b32_e32 v30, 16, v20
	v_and_b32_e32 v31, 0xffff0000, v20
	v_add_f32_e32 v16, 1.0, v16
	v_pk_fma_f32 v[26:27], v[100:101], v[30:31], v[26:27]
	v_rcp_f32_e32 v23, v16
	v_mul_f32_e32 v16, 0xbfb8aa3b, v26
	v_lshlrev_b32_e32 v32, 16, v33
	v_and_b32_e32 v33, 0xffff0000, v33
	v_exp_f32_e32 v16, v16
	v_pk_fma_f32 v[32:33], v[56:57], v[32:33], 0 op_sel_hi:[1,1,0]
	v_lshlrev_b32_e32 v28, 16, v29
	v_and_b32_e32 v29, 0xffff0000, v29
	v_pk_fma_f32 v[28:29], v[62:63], v[28:29], v[32:33]
	v_lshlrev_b32_e32 v24, 16, v25
	v_and_b32_e32 v25, 0xffff0000, v25
	v_pk_fma_f32 v[24:25], v[68:69], v[24:25], v[28:29]
	v_lshlrev_b32_e32 v28, 16, v12
	v_and_b32_e32 v29, 0xffff0000, v12
	v_pk_fma_f32 v[28:29], v[54:55], v[28:29], 0 op_sel_hi:[1,1,0]
	v_lshlrev_b32_e32 v32, 16, v8
	v_and_b32_e32 v33, 0xffff0000, v8
	v_add_f32_e32 v16, 1.0, v16
	v_pk_fma_f32 v[28:29], v[60:61], v[32:33], v[28:29]
	v_lshlrev_b32_e32 v32, 16, v4
	v_and_b32_e32 v33, 0xffff0000, v4
	v_rcp_f32_e32 v30, v16
	v_mul_f32_e32 v16, 0xbfb8aa3b, v27
	v_pk_fma_f32 v[28:29], v[64:65], v[32:33], v[28:29]
	v_lshlrev_b32_e32 v32, 16, v0
	v_and_b32_e32 v33, 0xffff0000, v0
	v_exp_f32_e32 v16, v16
	v_pk_fma_f32 v[28:29], v[90:91], v[32:33], v[28:29]
	v_pk_mul_f32 v[94:95], v[38:39], v[124:125] op_sel_hi:[0,1]
	v_mul_f32_e32 v0, 0xbfb8aa3b, v28
	v_exp_f32_e32 v0, v0
	v_lshlrev_b32_e32 v20, 16, v21
	v_and_b32_e32 v21, 0xffff0000, v21
	v_pk_mul_f32 v[126:127], v[38:39], v[126:127] op_sel_hi:[0,1]
	v_add_f32_e32 v16, 1.0, v16
	v_pk_fma_f32 v[20:21], v[94:95], v[20:21], v[24:25]
	v_pk_fma_f32 v[10:11], v[126:127], v[14:15], v[10:11]
	v_rcp_f32_e32 v31, v16
	v_mul_f32_e32 v16, 0xbfb8aa3b, v20
	v_mul_f32_e32 v14, 0xbfb8aa3b, v10
	v_mul_f32_e32 v15, 0xbfb8aa3b, v11
	v_exp_f32_e32 v16, v16
	v_add_f32_e32 v0, 1.0, v0
	v_exp_f32_e32 v14, v14
	v_exp_f32_e32 v15, v15
	v_rcp_f32_e32 v32, v0
	v_mul_f32_e32 v0, 0xbfb8aa3b, v29
	v_exp_f32_e32 v0, v0
	v_add_f32_e32 v16, 1.0, v16
	v_lshlrev_b32_e32 v12, 16, v13
	v_and_b32_e32 v13, 0xffff0000, v13
	v_add_f32_e32 v14, 1.0, v14
	v_add_f32_e32 v15, 1.0, v15
	v_rcp_f32_e32 v24, v16
	v_mul_f32_e32 v16, 0xbfb8aa3b, v21
	v_pk_fma_f32 v[12:13], v[34:35], v[12:13], 0 op_sel_hi:[1,1,0]
	v_lshlrev_b32_e32 v8, 16, v9
	v_and_b32_e32 v9, 0xffff0000, v9
	v_rcp_f32_e32 v14, v14
	v_rcp_f32_e32 v15, v15
	v_exp_f32_e32 v16, v16
	v_add_f32_e32 v0, 1.0, v0
	v_pk_fma_f32 v[8:9], v[36:37], v[8:9], v[12:13]
	v_lshlrev_b32_e32 v4, 16, v5
	v_and_b32_e32 v5, 0xffff0000, v5
	v_pk_mul_f32 v[76:77], v[38:39], v[120:121] op_sel_hi:[0,1]
	v_mul_f32_e32 v6, 0xbfb8aa3b, v3
	v_rcp_f32_e32 v33, v0
	v_pk_fma_f32 v[4:5], v[58:59], v[4:5], v[8:9]
	v_lshlrev_b32_e32 v0, 16, v1
	v_and_b32_e32 v1, 0xffff0000, v1
	v_exp_f32_e32 v6, v6
	v_pk_fma_f32 v[0:1], v[76:77], v[0:1], v[4:5]
	v_pk_mul_f32 v[10:11], v[10:11], v[14:15]
	v_mul_f32_e32 v4, 0xbfb8aa3b, v0
	v_mul_f32_e32 v5, 0xbfb8aa3b, v1
	v_add_f32_e32 v16, 1.0, v16
	v_exp_f32_e32 v4, v4
	v_exp_f32_e32 v5, v5
	v_pk_mul_f32 v[14:15], v[10:11], v[10:11]
	v_pk_mul_f32 v[18:19], v[18:19], v[22:23]
	v_rcp_f32_e32 v25, v16
	v_add_f32_e32 v6, 1.0, v6
	v_pk_mul_f32 v[22:23], v[18:19], v[18:19]
	v_add_f32_e32 v8, v14, v15
	v_rcp_f32_e32 v7, v6
	v_mul_f32_e32 v6, 0xbfb8aa3b, v2
	v_pk_mul_f32 v[26:27], v[26:27], v[30:31]
	v_add_f32_e32 v8, v22, v8
	v_exp_f32_e32 v6, v6
	v_pk_mul_f32 v[30:31], v[26:27], v[26:27]
	v_add_f32_e32 v4, 1.0, v4
	v_add_f32_e32 v5, 1.0, v5
	v_add_f32_e32 v8, v23, v8
	v_pk_mul_f32 v[20:21], v[20:21], v[24:25]
	v_rcp_f32_e32 v4, v4
	v_rcp_f32_e32 v5, v5
	v_add_f32_e32 v8, v30, v8
	v_pk_mul_f32 v[24:25], v[20:21], v[20:21]
	v_add_f32_e32 v8, v31, v8
	v_pk_mul_f32 v[28:29], v[28:29], v[32:33]
	v_add_f32_e32 v8, v24, v8
	v_add_f32_e32 v6, 1.0, v6
	v_pk_mul_f32 v[32:33], v[28:29], v[28:29]
	v_add_f32_e32 v8, v25, v8
	v_rcp_f32_e32 v6, v6
	v_pk_mul_f32 v[0:1], v[0:1], v[4:5]
	v_add_f32_e32 v8, v32, v8
	v_pk_mul_f32 v[4:5], v[0:1], v[0:1]
	v_add_f32_e32 v8, v33, v8
	v_pk_mul_f32 v[74:75], v[74:75], v[84:85]
	v_add_f32_e32 v4, v4, v8
	v_pk_mul_f32 v[84:85], v[74:75], v[74:75]
	v_add_f32_e32 v4, v5, v4
	v_pk_mul_f32 v[2:3], v[2:3], v[6:7]
	v_add_f32_e32 v4, v84, v4
	v_pk_mul_f32 v[6:7], v[2:3], v[2:3]
	v_add_f32_e32 v4, v85, v4
	v_add_f32_e32 v4, v6, v4
	v_add_f32_e32 v4, v7, v4
	ds_bpermute_b32 v5, v45, v4
	v_or_b32_e32 v34, 0x400, v39
	s_waitcnt lgkmcnt(0)
	v_add_f32_e32 v4, v4, v5
	ds_bpermute_b32 v5, v112, v4
	s_waitcnt lgkmcnt(0)
	v_add_f32_e32 v4, v4, v5
	ds_bpermute_b32 v5, v113, v4
	s_waitcnt lgkmcnt(0)
	v_add_f32_e32 v4, v4, v5
	v_add_f32_e32 v4, 0x358637bd, v4
	v_cmp_gt_f32_e32 vcc, s33, v4
	v_mul_f32_e32 v5, 0x4b800000, v4
	s_nop 0
	v_cndmask_b32_e32 v4, v4, v5, vcc
	v_rsq_f32_e32 v4, v4
	s_nop 0
	v_mul_f32_e32 v5, 0x45800000, v4
	v_cndmask_b32_e32 v16, v4, v5, vcc
	v_pk_mul_f32 v[4:5], v[10:11], v[16:17] op_sel_hi:[1,0]
	v_pk_mul_f32 v[6:7], v[18:19], v[16:17] op_sel_hi:[1,0]
	v_pk_mul_f32 v[8:9], v[26:27], v[16:17] op_sel_hi:[1,0]
	v_pk_mul_f32 v[10:11], v[20:21], v[16:17] op_sel_hi:[1,0]
	v_pk_mul_f32 v[12:13], v[28:29], v[16:17] op_sel_hi:[1,0]
	v_pk_mul_f32 v[14:15], v[0:1], v[16:17] op_sel_hi:[1,0]
	v_pk_mul_f32 v[0:1], v[74:75], v[16:17] op_sel_hi:[1,0]
	v_pk_mul_f32 v[2:3], v[2:3], v[16:17] op_sel_hi:[1,0]
	v_cvt_pk_bf16_f32 v16, v4, v5
	v_cvt_pk_bf16_f32 v18, v6, v7
	ds_write2_b32 v43, v16, v18 offset1:1
	v_cvt_pk_bf16_f32 v16, v8, v9
	v_cvt_pk_bf16_f32 v18, v10, v11
	ds_write2_b32 v43, v16, v18 offset0:2 offset1:3
	v_cvt_pk_bf16_f32 v16, v12, v13
	v_cvt_pk_bf16_f32 v18, v14, v15
	ds_write2_b32 v43, v16, v18 offset0:4 offset1:5
	v_cvt_pk_bf16_f32 v16, v0, v1
	v_cvt_pk_bf16_f32 v18, v2, v3
	ds_write2_b32 v43, v16, v18 offset0:6 offset1:7
	ds_write_b128 v110, v[4:7] offset:35328
	ds_write_b128 v110, v[8:11] offset:35344
	ds_write_b128 v110, v[12:15] offset:35360
	ds_write_b128 v110, v[0:3] offset:35376
	v_lshlrev_b32_e32 v16, 1, v34
	v_lshl_add_u64 v[0:1], v[46:47], 0, v[16:17]
	global_load_dwordx4 v[12:15], v[0:1], off
	global_load_dwordx4 v[30:33], v[0:1], off offset:16
	v_lshl_add_u64 v[0:1], v[48:49], 0, v[16:17]
	global_load_dwordx4 v[8:11], v[0:1], off
	global_load_dwordx4 v[26:29], v[0:1], off offset:16
	v_lshl_add_u64 v[0:1], v[50:51], 0, v[16:17]
	v_lshl_add_u64 v[18:19], v[52:53], 0, v[16:17]
	global_load_dwordx4 v[4:7], v[0:1], off
	global_load_dwordx4 v[22:25], v[0:1], off offset:16
	s_nop 0
	global_load_dwordx4 v[0:3], v[18:19], off
	s_nop 0
	global_load_dwordx4 v[18:21], v[18:19], off offset:16
	s_mov_b32 s8, 0
	s_ashr_i32 s9, s8, 31
	s_lshl_b64 s[8:9], s[8:9], 3
	s_add_u32 s8, s0, s8
	s_addc_u32 s9, s1, s9
	s_load_dwordx2 s[8:9], s[8:9], 0x90
	v_lshlrev_b32_e32 v16, 2, v34
	v_cmp_gt_u32_e32 vcc, 64, v106
	s_waitcnt lgkmcnt(0)
	s_add_u32 s98, s8, s16
	s_addc_u32 s99, s9, s17
	s_add_u32 s100, s8, s18
	s_addc_u32 s101, s9, s19
	s_add_u32 s30, s8, s22
	s_addc_u32 s31, s9, s23
	s_add_u32 s8, s8, s15
	s_addc_u32 s9, s9, s14
	global_load_dwordx4 v[52:55], v16, s[8:9] offset:48
	global_load_dwordx4 v[56:59], v16, s[8:9] offset:32
	global_load_dwordx4 v[48:51], v16, s[8:9] offset:16
	global_load_dwordx4 v[34:37], v16, s[8:9]
	global_load_dwordx4 v[140:143], v16, s[98:99] offset:48
	global_load_dwordx4 v[144:147], v16, s[98:99] offset:32
	global_load_dwordx4 v[148:151], v16, s[98:99] offset:16
	global_load_dwordx4 v[152:155], v16, s[98:99]
	global_load_dwordx4 v[156:159], v16, s[100:101] offset:48
	global_load_dwordx4 v[160:163], v16, s[100:101] offset:32
	global_load_dwordx4 v[164:167], v16, s[100:101] offset:16
	global_load_dwordx4 v[168:171], v16, s[100:101]
	global_load_dwordx4 v[172:175], v16, s[30:31] offset:48
	global_load_dwordx4 v[176:179], v16, s[30:31] offset:32
	global_load_dwordx4 v[180:183], v16, s[30:31] offset:16
	global_load_dwordx4 v[184:187], v16, s[30:31]
	s_mov_b32 s8, 0
	s_ashr_i32 s9, s8, 31
	s_lshl_b64 s[8:9], s[8:9], 3
	s_add_u32 s8, s0, s8
	s_addc_u32 s9, s1, s9
	s_waitcnt lgkmcnt(0)
	s_add_u32 s8, s8, s16
	s_addc_u32 s9, s9, s17
	s_waitcnt vmcnt(0)
	v_pk_mul_f32 v[70:71], v[44:45], v[52:53] op_sel_hi:[0,1]
	v_pk_mul_f32 v[56:57], v[44:45], v[56:57] op_sel_hi:[0,1]
	v_pk_mul_f32 v[48:49], v[44:45], v[48:49] op_sel_hi:[0,1]
	v_pk_mul_f32 v[34:35], v[44:45], v[34:35] op_sel_hi:[0,1]
	v_pk_mul_f32 v[36:37], v[44:45], v[36:37] op_sel_hi:[0,1]
	v_pk_mul_f32 v[50:51], v[44:45], v[50:51] op_sel_hi:[0,1]
	v_pk_mul_f32 v[62:63], v[44:45], v[58:59] op_sel_hi:[0,1]
	v_pk_mul_f32 v[78:79], v[44:45], v[54:55] op_sel_hi:[0,1]
	v_mov_b64_e32 v[66:67], v[140:141]
	v_mov_b64_e32 v[68:69], v[142:143]
	v_mov_b64_e32 v[72:73], v[144:145]
	v_mov_b64_e32 v[74:75], v[146:147]
	v_mov_b64_e32 v[58:59], v[148:149]
	v_mov_b64_e32 v[60:61], v[150:151]
	v_mov_b64_e32 v[44:45], v[152:153]
	v_mov_b64_e32 v[46:47], v[154:155]
	s_mov_b32 s8, 0
	s_ashr_i32 s9, s8, 31
	s_lshl_b64 s[8:9], s[8:9], 3
	s_add_u32 s8, s0, s8
	s_addc_u32 s9, s1, s9
	s_waitcnt lgkmcnt(0)
	s_add_u32 s8, s8, s18
	s_addc_u32 s9, s9, s19
	s_waitcnt vmcnt(3)
	v_pk_mul_f32 v[80:81], v[42:43], v[66:67] op_sel_hi:[0,1]
	s_waitcnt vmcnt(2)
	v_pk_mul_f32 v[64:65], v[42:43], v[72:73] op_sel_hi:[0,1]
	v_pk_mul_f32 v[72:73], v[42:43], v[74:75] op_sel_hi:[0,1]
	v_pk_mul_f32 v[86:87], v[42:43], v[68:69] op_sel_hi:[0,1]
	v_mov_b64_e32 v[88:89], v[156:157]
	v_mov_b64_e32 v[90:91], v[158:159]
	v_mov_b64_e32 v[74:75], v[160:161]
	v_mov_b64_e32 v[76:77], v[162:163]
	v_mov_b64_e32 v[66:67], v[164:165]
	v_mov_b64_e32 v[68:69], v[166:167]
	v_mov_b64_e32 v[82:83], v[168:169]
	v_mov_b64_e32 v[84:85], v[170:171]
	s_mov_b32 s8, 0
	s_ashr_i32 s9, s8, 31
	s_lshl_b64 s[8:9], s[8:9], 3
	s_add_u32 s8, s0, s8
	s_addc_u32 s9, s1, s9
	s_waitcnt vmcnt(4)
	v_pk_mul_f32 v[44:45], v[42:43], v[44:45] op_sel_hi:[0,1]
	v_pk_mul_f32 v[46:47], v[42:43], v[46:47] op_sel_hi:[0,1]
	v_pk_mul_f32 v[54:55], v[42:43], v[58:59] op_sel_hi:[0,1]
	v_pk_mul_f32 v[58:59], v[42:43], v[60:61] op_sel_hi:[0,1]
	s_waitcnt lgkmcnt(0)
	s_add_u32 s8, s8, s22
	s_addc_u32 s9, s9, s23
	v_mov_b64_e32 v[92:93], v[172:173]
	v_mov_b64_e32 v[94:95], v[174:175]
	v_mov_b64_e32 v[96:97], v[176:177]
	v_mov_b64_e32 v[98:99], v[178:179]
	v_mov_b64_e32 v[100:101], v[180:181]
	v_mov_b64_e32 v[102:103], v[182:183]
	v_mov_b64_e32 v[112:113], v[184:185]
	v_mov_b64_e32 v[114:115], v[186:187]
	s_waitcnt vmcnt(7)
	v_pk_mul_f32 v[88:89], v[40:41], v[88:89] op_sel_hi:[0,1]
	s_waitcnt vmcnt(6)
	v_pk_mul_f32 v[74:75], v[40:41], v[74:75] op_sel_hi:[0,1]
	s_waitcnt vmcnt(5)
	v_pk_mul_f32 v[60:61], v[40:41], v[66:67] op_sel_hi:[0,1]
	s_waitcnt vmcnt(4)
	v_pk_mul_f32 v[42:43], v[40:41], v[82:83] op_sel_hi:[0,1]
	v_pk_mul_f32 v[52:53], v[40:41], v[84:85] op_sel_hi:[0,1]
	v_pk_mul_f32 v[66:67], v[40:41], v[68:69] op_sel_hi:[0,1]
	v_pk_mul_f32 v[82:83], v[40:41], v[76:77] op_sel_hi:[0,1]
	v_pk_mul_f32 v[40:41], v[40:41], v[90:91] op_sel_hi:[0,1]
	s_waitcnt vmcnt(3)
	v_pk_mul_f32 v[92:93], v[38:39], v[92:93] op_sel_hi:[0,1]
	s_waitcnt vmcnt(2)
	v_pk_mul_f32 v[96:97], v[38:39], v[96:97] op_sel_hi:[0,1]
	s_waitcnt vmcnt(1)
	v_pk_mul_f32 v[84:85], v[38:39], v[100:101] op_sel_hi:[0,1]
	s_waitcnt vmcnt(0)
	v_pk_mul_f32 v[68:69], v[38:39], v[112:113] op_sel_hi:[0,1]
	v_pk_mul_f32 v[76:77], v[38:39], v[114:115] op_sel_hi:[0,1]
	v_pk_mul_f32 v[90:91], v[38:39], v[102:103] op_sel_hi:[0,1]
	v_pk_mul_f32 v[98:99], v[38:39], v[98:99] op_sel_hi:[0,1]
	v_pk_mul_f32 v[38:39], v[38:39], v[94:95] op_sel_hi:[0,1]
	v_lshlrev_b32_e32 v94, 16, v33
	v_and_b32_e32 v95, 0xffff0000, v33
	v_pk_fma_f32 v[78:79], v[78:79], v[94:95], 0 op_sel_hi:[1,1,0]
	v_lshlrev_b32_e32 v94, 16, v29
	v_and_b32_e32 v95, 0xffff0000, v29
	v_pk_fma_f32 v[78:79], v[86:87], v[94:95], v[78:79]
	v_lshlrev_b32_e32 v86, 16, v25
	v_and_b32_e32 v87, 0xffff0000, v25
	v_pk_fma_f32 v[40:41], v[40:41], v[86:87], v[78:79]
	v_lshlrev_b32_e32 v78, 16, v21
	v_and_b32_e32 v79, 0xffff0000, v21
	v_pk_fma_f32 v[38:39], v[38:39], v[78:79], v[40:41]
	v_lshlrev_b32_e32 v78, 16, v32
	v_and_b32_e32 v79, 0xffff0000, v32
	v_pk_fma_f32 v[32:33], v[70:71], v[78:79], 0 op_sel_hi:[1,1,0]
	v_lshlrev_b32_e32 v70, 16, v28
	v_and_b32_e32 v71, 0xffff0000, v28
	v_pk_fma_f32 v[28:29], v[80:81], v[70:71], v[32:33]
	v_lshlrev_b32_e32 v32, 16, v24
	v_and_b32_e32 v33, 0xffff0000, v24
	v_pk_fma_f32 v[24:25], v[88:89], v[32:33], v[28:29]
	v_lshlrev_b32_e32 v28, 16, v20
	v_and_b32_e32 v29, 0xffff0000, v20
	v_pk_fma_f32 v[20:21], v[92:93], v[28:29], v[24:25]
	v_lshlrev_b32_e32 v28, 16, v31
	v_and_b32_e32 v29, 0xffff0000, v31
	v_pk_fma_f32 v[28:29], v[62:63], v[28:29], 0 op_sel_hi:[1,1,0]
	v_lshlrev_b32_e32 v62, 16, v30
	v_and_b32_e32 v63, 0xffff0000, v30
	v_pk_fma_f32 v[30:31], v[56:57], v[62:63], 0 op_sel_hi:[1,1,0]
	v_lshlrev_b32_e32 v56, 16, v26
	v_and_b32_e32 v57, 0xffff0000, v26
	v_lshlrev_b32_e32 v32, 16, v27
	v_and_b32_e32 v33, 0xffff0000, v27
	v_pk_fma_f32 v[26:27], v[64:65], v[56:57], v[30:31]
	v_lshlrev_b32_e32 v30, 16, v22
	v_and_b32_e32 v31, 0xffff0000, v22
	v_pk_fma_f32 v[28:29], v[72:73], v[32:33], v[28:29]
	v_lshlrev_b32_e32 v32, 16, v23
	v_and_b32_e32 v33, 0xffff0000, v23
	v_pk_fma_f32 v[22:23], v[74:75], v[30:31], v[26:27]
	v_lshlrev_b32_e32 v26, 16, v18
	v_and_b32_e32 v27, 0xffff0000, v18
	v_pk_fma_f32 v[28:29], v[82:83], v[32:33], v[28:29]
	v_lshlrev_b32_e32 v32, 16, v19
	v_and_b32_e32 v33, 0xffff0000, v19
	v_pk_fma_f32 v[18:19], v[96:97], v[26:27], v[22:23]
	v_lshlrev_b32_e32 v26, 16, v15
	v_and_b32_e32 v27, 0xffff0000, v15
	v_pk_fma_f32 v[26:27], v[50:51], v[26:27], 0 op_sel_hi:[1,1,0]
	v_lshlrev_b32_e32 v50, 16, v14
	v_and_b32_e32 v51, 0xffff0000, v14
	v_mul_f32_e32 v16, 0xbfb8aa3b, v39
	v_lshlrev_b32_e32 v30, 16, v11
	v_and_b32_e32 v31, 0xffff0000, v11
	v_pk_fma_f32 v[14:15], v[48:49], v[50:51], 0 op_sel_hi:[1,1,0]
	v_lshlrev_b32_e32 v48, 16, v10
	v_and_b32_e32 v49, 0xffff0000, v10
	v_exp_f32_e32 v16, v16
	v_pk_fma_f32 v[26:27], v[58:59], v[30:31], v[26:27]
	v_lshlrev_b32_e32 v30, 16, v7
	v_and_b32_e32 v31, 0xffff0000, v7
	v_pk_fma_f32 v[10:11], v[54:55], v[48:49], v[14:15]
	v_lshlrev_b32_e32 v14, 16, v6
	v_and_b32_e32 v15, 0xffff0000, v6
	v_pk_fma_f32 v[26:27], v[66:67], v[30:31], v[26:27]
	v_lshlrev_b32_e32 v30, 16, v3
	v_and_b32_e32 v31, 0xffff0000, v3
	v_pk_fma_f32 v[6:7], v[60:61], v[14:15], v[10:11]
	v_lshlrev_b32_e32 v10, 16, v2
	v_and_b32_e32 v11, 0xffff0000, v2
	v_pk_fma_f32 v[26:27], v[90:91], v[30:31], v[26:27]
	v_pk_fma_f32 v[6:7], v[84:85], v[10:11], v[6:7]
	v_mul_f32_e32 v3, 0xbfb8aa3b, v27
	v_mul_f32_e32 v2, 0xbfb8aa3b, v7
	v_add_f32_e32 v16, 1.0, v16
	v_exp_f32_e32 v3, v3
	v_exp_f32_e32 v2, v2
	v_rcp_f32_e32 v41, v16
	v_mul_f32_e32 v16, 0xbfb8aa3b, v38
	v_exp_f32_e32 v16, v16
	v_add_f32_e32 v3, 1.0, v3
	v_add_f32_e32 v2, 1.0, v2
	v_rcp_f32_e32 v31, v3
	v_mul_f32_e32 v3, 0xbfb8aa3b, v26
	v_rcp_f32_e32 v11, v2
	v_mul_f32_e32 v2, 0xbfb8aa3b, v6
	v_add_f32_e32 v16, 1.0, v16
	v_exp_f32_e32 v3, v3
	v_exp_f32_e32 v2, v2
	v_rcp_f32_e32 v40, v16
	v_mul_f32_e32 v16, 0xbfb8aa3b, v21
	v_exp_f32_e32 v16, v16
	v_add_f32_e32 v3, 1.0, v3
	v_add_f32_e32 v2, 1.0, v2
	v_rcp_f32_e32 v30, v3
	v_rcp_f32_e32 v10, v2
	v_lshlrev_b32_e32 v2, 16, v13
	v_and_b32_e32 v3, 0xffff0000, v13
	v_add_f32_e32 v16, 1.0, v16
	v_pk_fma_f32 v[2:3], v[36:37], v[2:3], 0 op_sel_hi:[1,1,0]
	v_lshlrev_b32_e32 v14, 16, v9
	v_and_b32_e32 v15, 0xffff0000, v9
	v_rcp_f32_e32 v25, v16
	v_mul_f32_e32 v16, 0xbfb8aa3b, v20
	v_pk_fma_f32 v[2:3], v[46:47], v[14:15], v[2:3]
	v_lshlrev_b32_e32 v14, 16, v5
	v_and_b32_e32 v15, 0xffff0000, v5
	v_exp_f32_e32 v16, v16
	v_pk_fma_f32 v[2:3], v[52:53], v[14:15], v[2:3]
	v_lshlrev_b32_e32 v14, 16, v1
	v_and_b32_e32 v15, 0xffff0000, v1
	v_pk_fma_f32 v[2:3], v[76:77], v[14:15], v[2:3]
	v_add_f32_e32 v16, 1.0, v16
	v_mul_f32_e32 v1, 0xbfb8aa3b, v3
	v_exp_f32_e32 v1, v1
	v_pk_fma_f32 v[28:29], v[98:99], v[32:33], v[28:29]
	v_rcp_f32_e32 v24, v16
	v_mul_f32_e32 v16, 0xbfb8aa3b, v29
	v_exp_f32_e32 v16, v16
	v_add_f32_e32 v1, 1.0, v1
	v_rcp_f32_e32 v15, v1
	v_mul_f32_e32 v1, 0xbfb8aa3b, v2
	v_exp_f32_e32 v1, v1
	v_add_f32_e32 v16, 1.0, v16
	v_lshlrev_b32_e32 v36, 16, v12
	v_and_b32_e32 v37, 0xffff0000, v12
	v_rcp_f32_e32 v33, v16
	v_mul_f32_e32 v16, 0xbfb8aa3b, v28
	v_pk_fma_f32 v[12:13], v[34:35], v[36:37], 0 op_sel_hi:[1,1,0]
	v_lshlrev_b32_e32 v34, 16, v8
	v_and_b32_e32 v35, 0xffff0000, v8
	v_exp_f32_e32 v16, v16
	v_pk_fma_f32 v[8:9], v[44:45], v[34:35], v[12:13]
	v_lshlrev_b32_e32 v12, 16, v4
	v_and_b32_e32 v13, 0xffff0000, v4
	v_add_f32_e32 v1, 1.0, v1
	v_pk_fma_f32 v[4:5], v[42:43], v[12:13], v[8:9]
	v_lshlrev_b32_e32 v8, 16, v0
	v_and_b32_e32 v9, 0xffff0000, v0
	v_rcp_f32_e32 v14, v1
	v_pk_fma_f32 v[0:1], v[68:69], v[8:9], v[4:5]
	v_add_f32_e32 v16, 1.0, v16
	v_mul_f32_e32 v4, 0xbfb8aa3b, v1
	v_exp_f32_e32 v4, v4
	v_rcp_f32_e32 v32, v16
	v_mul_f32_e32 v16, 0xbfb8aa3b, v19
	v_exp_f32_e32 v16, v16
	v_add_f32_e32 v4, 1.0, v4
	v_rcp_f32_e32 v5, v4
	v_mul_f32_e32 v4, 0xbfb8aa3b, v0
	v_add_f32_e32 v16, 1.0, v16
	v_exp_f32_e32 v4, v4
	v_rcp_f32_e32 v23, v16
	v_mul_f32_e32 v16, 0xbfb8aa3b, v18
	v_exp_f32_e32 v16, v16
	v_add_f32_e32 v4, 1.0, v4
	v_rcp_f32_e32 v4, v4
	v_pk_mul_f32 v[2:3], v[2:3], v[14:15]
	v_add_f32_e32 v16, 1.0, v16
	v_rcp_f32_e32 v22, v16
	v_pk_mul_f32 v[0:1], v[0:1], v[4:5]
	ds_write_b128 v110, v[0:3] offset:34816
	v_pk_mul_f32 v[0:1], v[6:7], v[10:11]
	v_pk_mul_f32 v[2:3], v[26:27], v[30:31]
	ds_write_b128 v110, v[0:3] offset:34832
	v_pk_mul_f32 v[0:1], v[18:19], v[22:23]
	v_pk_mul_f32 v[2:3], v[28:29], v[32:33]
	ds_write_b128 v110, v[0:3] offset:34848
	v_pk_mul_f32 v[0:1], v[20:21], v[24:25]
	v_pk_mul_f32 v[2:3], v[38:39], v[40:41]
	v_lshl_add_u32 v44, v106, 2, 0
	ds_write_b128 v110, v[0:3] offset:34864
	s_and_saveexec_b64 s[8:9], vcc
	s_cbranch_execz .LBB0_763
	v_or_b32_e32 v0, s5, v106
	v_ashrrev_i32_e32 v1, 31, v0
	v_lshlrev_b64 v[0:1], 5, v[0:1]
	v_lshl_add_u64 v[0:1], s[42:43], 0, v[0:1]
	s_lshl_b32 s52, s37, 2
	v_lshl_add_u64 v[0:1], v[0:1], 0, s[52:53]
	v_mov_b32_e32 v2, v189
	s_nop 0
	v_mov_b32_e32 v0, v190
	s_mov_b32 s38, 0
	s_ashr_i32 s39, s38, 31
	s_lshl_b64 s[38:39], s[38:39], 3
	s_add_u32 s38, s0, s38
	s_addc_u32 s39, s1, s39
	s_or_b32 s48, s37, s35
	s_ashr_i32 s49, s48, 31
	s_lshl_b64 s[48:49], s[48:49], 2
	s_mov_b32 s2, 0xbfb8aa3b
	s_waitcnt lgkmcnt(0)
	s_add_u32 s38, s38, s48
	s_addc_u32 s39, s39, s49
	v_mov_b32_e32 v1, v191
	s_mov_b32 s38, 0
	s_ashr_i32 s39, s38, 31
	s_lshl_b64 s[38:39], s[38:39], 3
	s_add_u32 s38, s0, s38
	s_addc_u32 s39, s1, s39
	s_waitcnt lgkmcnt(0)
	s_add_u32 s38, s38, s48
	s_addc_u32 s39, s39, s49
	v_mov_b32_e32 v3, v192
	s_waitcnt vmcnt(0)
	v_mul_f32_e32 v0, 0xbfb8aa3b, v0
	v_exp_f32_e32 v0, v0
	v_mul_f32_e32 v1, 0x3fb8aa3b, v1
	v_exp_f32_e32 v1, v1
	v_add_f32_e32 v0, 1.0, v0
	v_rcp_f32_e32 v0, v0
	v_add_f32_e32 v2, v2, v3
	v_max_f32_e32 v4, 0, v2
	v_mul_f32_e64 v2, |v2|, s2
	v_exp_f32_e32 v5, v2
	s_mov_b32 s2, 0x3f2aaaab
	v_add_f32_e32 v6, 1.0, v5
	v_add_f32_e32 v2, -1.0, v6
	v_sub_f32_e32 v3, v2, v6
	v_add_f32_e32 v3, 1.0, v3
	v_sub_f32_e32 v2, v5, v2
	v_add_f32_e32 v7, v2, v3
	v_frexp_mant_f32_e32 v2, v6
	v_cmp_gt_f32_e32 vcc, s2, v2
	v_cvt_f64_f32_e32 v[2:3], v6
	v_frexp_exp_i32_f64_e32 v2, v[2:3]
	v_subbrev_co_u32_e32 v2, vcc, 0, v2, vcc
	v_sub_u32_e32 v3, 0, v2
	v_ldexp_f32 v6, v6, v3
	v_ldexp_f32 v3, v7, v3
	v_add_f32_e32 v7, -1.0, v6
	v_add_f32_e32 v8, 1.0, v7
	v_sub_f32_e32 v8, v6, v8
	v_add_f32_e32 v8, v3, v8
	v_add_f32_e32 v9, v7, v8
	v_sub_f32_e32 v7, v9, v7
	v_sub_f32_e32 v7, v8, v7
	v_add_f32_e32 v8, 1.0, v6
	v_add_f32_e32 v10, -1.0, v8
	v_sub_f32_e32 v6, v6, v10
	v_add_f32_e32 v3, v3, v6
	v_add_f32_e32 v6, v8, v3
	v_sub_f32_e32 v8, v6, v8
	v_sub_f32_e32 v3, v3, v8
	v_rcp_f32_e32 v8, v6
	v_cvt_f32_i32_e32 v2, v2
	s_mov_b32 s2, 0x3f317218
	v_mul_f32_e32 v10, v9, v8
	v_mul_f32_e32 v11, v6, v10
	v_fma_f32 v12, v10, v6, -v11
	v_fmac_f32_e32 v12, v10, v3
	v_add_f32_e32 v13, v11, v12
	v_sub_f32_e32 v14, v9, v13
	v_sub_f32_e32 v9, v9, v14
	v_sub_f32_e32 v11, v13, v11
	v_sub_f32_e32 v9, v9, v13
	v_add_f32_e32 v7, v7, v9
	v_sub_f32_e32 v9, v11, v12
	v_add_f32_e32 v7, v9, v7
	v_add_f32_e32 v9, v14, v7
	v_mul_f32_e32 v11, v8, v9
	v_mul_f32_e32 v12, v6, v11
	v_fma_f32 v6, v11, v6, -v12
	v_fmac_f32_e32 v6, v11, v3
	v_sub_f32_e32 v3, v14, v9
	v_add_f32_e32 v3, v7, v3
	v_add_f32_e32 v7, v12, v6
	v_sub_f32_e32 v13, v9, v7
	v_sub_f32_e32 v9, v9, v13
	v_sub_f32_e32 v12, v7, v12
	v_sub_f32_e32 v7, v9, v7
	v_add_f32_e32 v3, v3, v7
	v_sub_f32_e32 v6, v12, v6
	v_add_f32_e32 v3, v6, v3
	v_add_f32_e32 v6, v10, v11
	v_add_f32_e32 v3, v13, v3
	v_sub_f32_e32 v7, v6, v10
	v_mul_f32_e32 v3, v8, v3
	v_sub_f32_e32 v7, v11, v7
	v_add_f32_e32 v3, v7, v3
	v_mul_f32_e32 v10, 0x3f317218, v2
	v_add_f32_e32 v7, v6, v3
	v_fma_f32 v11, v2, s2, -v10
	v_mul_f32_e32 v8, v7, v7
	v_fmac_f32_e32 v11, 0xb102e308, v2
	v_sub_f32_e32 v2, v7, v6
	v_fmamk_f32 v9, v8, 0x3e9b6dac, v232
	v_sub_f32_e32 v2, v3, v2
	v_add_f32_e32 v3, v10, v11
	v_fmaak_f32 v9, v8, v9, 0x3f2aaada
	v_sub_f32_e32 v6, v3, v10
	v_ldexp_f32 v10, v7, 1
	v_mul_f32_e32 v7, v7, v8
	v_mul_f32_e32 v7, v7, v9
	v_add_f32_e32 v8, v10, v7
	v_sub_f32_e32 v9, v8, v10
	v_ldexp_f32 v2, v2, 1
	v_sub_f32_e32 v7, v7, v9
	v_add_f32_e32 v2, v2, v7
	v_add_f32_e32 v7, v8, v2
	v_sub_f32_e32 v8, v7, v8
	v_sub_f32_e32 v2, v2, v8
	v_add_f32_e32 v8, v3, v7
	v_sub_f32_e32 v9, v8, v3
	v_sub_f32_e32 v10, v8, v9
	v_sub_f32_e32 v6, v11, v6
	v_sub_f32_e32 v3, v3, v10
	v_sub_f32_e32 v7, v7, v9
	v_add_f32_e32 v3, v7, v3
	v_add_f32_e32 v7, v6, v2
	v_sub_f32_e32 v9, v7, v6
	v_sub_f32_e32 v10, v7, v9
	v_sub_f32_e32 v6, v6, v10
	v_sub_f32_e32 v2, v2, v9
	v_add_f32_e32 v3, v7, v3
	v_add_f32_e32 v2, v2, v6
	v_add_f32_e32 v6, v8, v3
	v_sub_f32_e32 v7, v6, v8
	v_sub_f32_e32 v3, v3, v7
	v_add_f32_e32 v2, v2, v3
	s_mov_b32 s2, 0x7f800000
	v_add_f32_e32 v2, v6, v2
	v_cmp_neq_f32_e32 vcc, s2, v5
	s_mov_b32 s2, 0x33800000
	s_nop 0
	v_cndmask_b32_e32 v2, v236, v2, vcc
	v_cmp_ngt_f32_e32 vcc, -1.0, v5
	s_nop 1
	v_cndmask_b32_e32 v2, v237, v2, vcc
	v_cmp_neq_f32_e32 vcc, -1.0, v5
	s_nop 1
	v_cndmask_b32_e32 v2, v238, v2, vcc
	v_cmp_lt_f32_e64 vcc, |v5|, s2
	s_nop 1
	v_cndmask_b32_e32 v2, v2, v5, vcc
	v_add_f32_e32 v2, v4, v2
	v_add_u32_e32 v4, -1, v234
	v_cmp_lt_i32_e32 vcc, v4, v111
	v_mul_f32_e64 v3, v2, -v1
	s_nop 0
	v_cndmask_b32_e32 v4, v4, v234, vcc
	v_lshlrev_b32_e32 v4, 2, v4
	ds_bpermute_b32 v4, v4, v3
	v_cmp_eq_u32_e32 vcc, 0, v106
	s_waitcnt lgkmcnt(0)
	v_fma_f32 v1, v2, -v1, v4
	v_add_u32_e32 v2, -2, v234
	v_cndmask_b32_e32 v1, v1, v3, vcc
	v_cmp_lt_i32_e32 vcc, v2, v111
	v_add_u32_e32 v3, 0x1cc00, v44
	s_nop 0
	v_cndmask_b32_e32 v2, v2, v234, vcc
	v_lshlrev_b32_e32 v2, 2, v2
	ds_bpermute_b32 v2, v2, v1
	v_cmp_gt_u32_e32 vcc, 2, v106
	s_waitcnt lgkmcnt(0)
	v_add_f32_e32 v2, v1, v2
	v_cndmask_b32_e32 v1, v2, v1, vcc
	v_add_u32_e32 v2, -4, v234
	v_cmp_lt_i32_e32 vcc, v2, v111
	s_nop 1
	v_cndmask_b32_e32 v2, v2, v234, vcc
	v_lshlrev_b32_e32 v2, 2, v2
	ds_bpermute_b32 v2, v2, v1
	v_cmp_gt_u32_e32 vcc, 4, v106
	s_waitcnt lgkmcnt(0)
	v_add_f32_e32 v2, v1, v2
	v_cndmask_b32_e32 v1, v2, v1, vcc
	v_add_u32_e32 v2, -8, v234
	v_cmp_lt_i32_e32 vcc, v2, v111
	s_nop 1
	v_cndmask_b32_e32 v2, v2, v234, vcc
	v_lshlrev_b32_e32 v2, 2, v2
	ds_bpermute_b32 v2, v2, v1
	v_cmp_gt_u32_e32 vcc, 8, v106
	s_waitcnt lgkmcnt(0)
	v_add_f32_e32 v2, v1, v2
	v_cndmask_b32_e32 v1, v2, v1, vcc
	v_add_u32_e32 v2, -16, v234
	v_cmp_lt_i32_e32 vcc, v2, v111
	s_nop 1
	v_cndmask_b32_e32 v2, v2, v234, vcc
	v_lshlrev_b32_e32 v2, 2, v2
	ds_bpermute_b32 v2, v2, v1
	v_cmp_gt_u32_e32 vcc, 16, v106
	s_waitcnt lgkmcnt(0)
	v_add_f32_e32 v2, v1, v2
	v_cndmask_b32_e32 v2, v2, v1, vcc
	v_subrev_u32_e32 v1, 32, v234
	v_cmp_lt_i32_e32 vcc, v1, v111
	s_nop 1
	v_cndmask_b32_e32 v1, v1, v234, vcc
	v_lshlrev_b32_e32 v1, 2, v1
	ds_bpermute_b32 v1, v1, v2
	v_cmp_gt_u32_e32 vcc, 32, v106
	s_waitcnt lgkmcnt(0)
	v_add_f32_e32 v1, v2, v1
	v_cndmask_b32_e32 v2, v1, v2, vcc
	ds_write_b32 v3, v2
	v_add_u32_e32 v2, 0x1cd00, v44
	v_cmp_eq_u32_e32 vcc, 63, v106
	ds_write_b32 v2, v0
	s_and_b64 exec, exec, vcc
	s_cbranch_execz .LBB0_763
	v_mul_f32_e32 v0, 0x3fb8aa3b, v1
	v_exp_f32_e32 v2, v0
	v_mov_b64_e32 v[0:1], s[92:93]
	global_store_dword v[0:1], v2, off
